# up-proj conv epilogue: lane shifts folded into v_fmac_f32_dpp (cur row_shr / prev row_shl) instead of 4 v_mov_b32_dpp + 3 v_pk_fma per value pair; on top of the prep de-serialisation
# speedup vs baseline: 1.0149x; 1.0032x over previous
; template <int CTRL> DI float dppf(float v) { return __int_as_float(__builtin_amdgcn_mov_dpp(__float_as_int(v), CTRL, 0xf, 0xf, true)); }
;     DI void operator()(pg8::f32x4 (&acc)[2][2][4][2], const pg8::Unit& u, int wr, int wc, int fr, int fq) const {
;     ...
;         for (int n = 0; n < 2; ++n) {
;             v4f w0[2], w1[2], w2[2], cb[2];
; #pragma unroll
;             for (int bj = 0; bj < 2; ++bj) {
;                 const float* p = cwp + u.pn * 256 + bj * 128 + wc * 32 + 8 * fq + 4 * n;
;                 w0[bj] = *(const v4f*)p; w1[bj] = *(const v4f*)(p + NUP); w2[bj] = *(const v4f*)(p + 2 * NUP); cb[bj] = *(const v4f*)(p + 3 * NUP);
;             }
; #pragma unroll
;             for (int ai = 0; ai < 2; ++ai) {
;                 v4f hal[2];
;                 {
;                     const bool has = (wr == 1) || (ai == 1);
;                     const int as = (wr == 1) ? ai : 0, ws_ = (wr == 1) ? 0 : 1;
; #pragma unroll
;                     for (int bj = 0; bj < 2; ++bj) { v4f hv = H[(((as * 2 + ws_) * 4 + wc) * 4 + bj * 2 + n) * 8 + hl]; hal[bj] = has ? hv : (v4f){0.f, 0.f, 0.f, 0.f}; }
;                 }
; #pragma unroll
;                 for (int m = 0; m < 4; ++m) {
;                     float cv[2][4];
; #pragma unroll
;                     for (int bj = 0; bj < 2; ++bj) {
;                         const pg8::f32x4 cur = acc[ai][bj][m][n];
;                         pg8::f32x4 prv;
;                         if (m > 0) prv = acc[ai][bj][m > 0 ? m - 1 : 0][n]; else prv = (pg8::f32x4){hal[bj][0], hal[bj][1], hal[bj][2], hal[bj][3]};
; #pragma unroll
;                         for (int i = 0; i < 4; ++i) {
;                             const float q1 = dppf<0x121>(prv[i]), q2 = dppf<0x122>(prv[i]);
;                             const float p1 = __int_as_float(__builtin_amdgcn_update_dpp(__float_as_int(q1), __float_as_int(cur[i]), 0x111, 0xf, 0xf, false));
;                             const float p2 = __int_as_float(__builtin_amdgcn_update_dpp(__float_as_int(q2), __float_as_int(cur[i]), 0x112, 0xf, 0xf, false));
;                             cv[bj][i] = cb[bj][i] + w0[bj][i] * p2 + w1[bj][i] * p1 + w2[bj][i] * cur[i];
;                         }
;                     }
.LBB0_257:
	s_ashr_i32 s28, s34, 12
	s_ashr_i32 s29, s28, 31
	s_and_b32 s23, s34, 0xfc0
	s_lshl_b64 s[24:25], s[28:29], 23
	s_cmpk_gt_u32 s23, 0xaff
	s_waitcnt lgkmcnt(0)
	v_or_b32_e32 v201, s23, v170
	s_cselect_b64 s[26:27], -1, 0
	s_waitcnt vmcnt(0)
	v_pk_fma_f32 v[212:213], v[158:159], v[130:131], v[134:135]
	v_fmac_f32_dpp v212, v158, v126 row_shr:1 row_mask:0xf bank_mask:0xf
	v_fmac_f32_dpp v212, v166, v126 row_shl:15 row_mask:0xf bank_mask:0xf
	v_fmac_f32_dpp v212, v158, v122 row_shr:2 row_mask:0xf bank_mask:0xf
	v_fmac_f32_dpp v212, v166, v122 row_shl:14 row_mask:0xf bank_mask:0xf
	v_fmac_f32_dpp v213, v159, v127 row_shr:1 row_mask:0xf bank_mask:0xf
	v_fmac_f32_dpp v213, v167, v127 row_shl:15 row_mask:0xf bank_mask:0xf
	v_fmac_f32_dpp v213, v159, v123 row_shr:2 row_mask:0xf bank_mask:0xf
	v_fmac_f32_dpp v213, v167, v123 row_shl:14 row_mask:0xf bank_mask:0xf
	v_pk_fma_f32 v[204:205], v[160:161], v[132:133], v[136:137]
	v_fmac_f32_dpp v204, v160, v128 row_shr:1 row_mask:0xf bank_mask:0xf
	v_fmac_f32_dpp v204, v168, v128 row_shl:15 row_mask:0xf bank_mask:0xf
	v_fmac_f32_dpp v204, v160, v124 row_shr:2 row_mask:0xf bank_mask:0xf
	v_fmac_f32_dpp v204, v168, v124 row_shl:14 row_mask:0xf bank_mask:0xf
	v_fmac_f32_dpp v205, v161, v129 row_shr:1 row_mask:0xf bank_mask:0xf
	v_fmac_f32_dpp v205, v169, v129 row_shl:15 row_mask:0xf bank_mask:0xf
	v_fmac_f32_dpp v205, v161, v125 row_shr:2 row_mask:0xf bank_mask:0xf
	v_fmac_f32_dpp v205, v169, v125 row_shl:14 row_mask:0xf bank_mask:0xf
	v_pk_fma_f32 v[166:167], v[156:157], v[116:117], v[120:121]
	v_fmac_f32_dpp v166, v156, v108 row_shr:1 row_mask:0xf bank_mask:0xf
	v_fmac_f32_dpp v166, v164, v108 row_shl:15 row_mask:0xf bank_mask:0xf
	v_fmac_f32_dpp v166, v156, v104 row_shr:2 row_mask:0xf bank_mask:0xf
	v_fmac_f32_dpp v166, v164, v104 row_shl:14 row_mask:0xf bank_mask:0xf
	v_fmac_f32_dpp v167, v157, v109 row_shr:1 row_mask:0xf bank_mask:0xf
	v_fmac_f32_dpp v167, v165, v109 row_shl:15 row_mask:0xf bank_mask:0xf
	v_fmac_f32_dpp v167, v157, v105 row_shr:2 row_mask:0xf bank_mask:0xf
	v_fmac_f32_dpp v167, v165, v105 row_shl:14 row_mask:0xf bank_mask:0xf
	v_pk_fma_f32 v[208:209], v[154:155], v[114:115], v[118:119]
	v_fmac_f32_dpp v208, v154, v106 row_shr:1 row_mask:0xf bank_mask:0xf
	v_fmac_f32_dpp v208, v162, v106 row_shl:15 row_mask:0xf bank_mask:0xf
	v_fmac_f32_dpp v208, v154, v102 row_shr:2 row_mask:0xf bank_mask:0xf
	v_fmac_f32_dpp v208, v162, v102 row_shl:14 row_mask:0xf bank_mask:0xf
	v_fmac_f32_dpp v209, v155, v107 row_shr:1 row_mask:0xf bank_mask:0xf
	v_fmac_f32_dpp v209, v163, v107 row_shl:15 row_mask:0xf bank_mask:0xf
	v_fmac_f32_dpp v209, v155, v103 row_shr:2 row_mask:0xf bank_mask:0xf
	v_fmac_f32_dpp v209, v163, v103 row_shl:14 row_mask:0xf bank_mask:0xf
	s_mov_b64 s[30:31], -1
	s_and_b64 vcc, exec, s[26:27]
	v_add_u32_e32 v195, 0xfffff500, v201
	s_cbranch_vccz .LBB0_259
	s_add_u32 s30, s55, s24
	s_addc_u32 s31, s58, s25
	s_mov_b64 s[30:31], 0

; DI unsigned pk2(float lo, float hi) { f32x2_t v = {lo, hi}; bf16x2_t b = __builtin_convertvector(v, bf16x2_t); return __builtin_bit_cast(unsigned, b); }
; template <int CTRL> DI float dppf(float v) { return __int_as_float(__builtin_amdgcn_mov_dpp(__float_as_int(v), CTRL, 0xf, 0xf, true)); }
;     DI void operator()(pg8::f32x4 (&acc)[2][2][4][2], const pg8::Unit& u, int wr, int wc, int fr, int fq) const {
;     ...
;                 for (int m = 0; m < 4; ++m) {
;                     float cv[2][4];
; #pragma unroll
;                     for (int bj = 0; bj < 2; ++bj) {
;                         const pg8::f32x4 cur = acc[ai][bj][m][n];
;                         pg8::f32x4 prv;
;                         if (m > 0) prv = acc[ai][bj][m > 0 ? m - 1 : 0][n]; else prv = (pg8::f32x4){hal[bj][0], hal[bj][1], hal[bj][2], hal[bj][3]};
; #pragma unroll
;                         for (int i = 0; i < 4; ++i) {
;                             const float q1 = dppf<0x121>(prv[i]), q2 = dppf<0x122>(prv[i]);
;                             const float p1 = __int_as_float(__builtin_amdgcn_update_dpp(__float_as_int(q1), __float_as_int(cur[i]), 0x111, 0xf, 0xf, false));
;                             const float p2 = __int_as_float(__builtin_amdgcn_update_dpp(__float_as_int(q2), __float_as_int(cur[i]), 0x112, 0xf, 0xf, false));
;                             cv[bj][i] = cb[bj][i] + w0[bj][i] * p2 + w1[bj][i] * p1 + w2[bj][i] * cur[i];
;                         }
;                     }
;                     float o[4];
; #pragma unroll
;                     for (int i = 0; i < 4; ++i) o[i] = gelu_tanh(cv[0][i]) * cv[1][i];
;                     const int row = u.pm * 256 + ai * 128 + wr * 64 + m * 16 + fr;
;                     v2u w; w.x = pk2(o[0], o[1]); w.y = pk2(o[2], o[3]);
;                     *(v2u*)(a_row(wsb, row) + u.pn * 128 + wc * 32 + 8 * fq + 4 * n) = w;
.LBB0_261:
	s_waitcnt vmcnt(1)
	v_mov_b64_e32 v[172:173], v[212:213]
	v_pk_mul_f32 v[212:213], v[172:173], v[172:173]
	v_pk_mul_f32 v[206:207], v[204:205], v[204:205]
	v_fmamk_f32 v64, v212, 0xbdd2d3e7, v175
	v_mul_f32_e32 v64, v172, v64
	v_fmamk_f32 v163, v213, 0xbdd2d3e7, v175
	v_exp_f32_e32 v64, v64
	v_mul_f32_e32 v163, v173, v163
	v_exp_f32_e32 v163, v163
	s_waitcnt vmcnt(0)
	v_add_f32_e32 v64, 1.0, v64
	v_rcp_f32_e32 v212, v64
	v_add_f32_e32 v64, 1.0, v163
	v_rcp_f32_e32 v213, v64
	v_fmamk_f32 v64, v206, 0xbdd2d3e7, v175
	v_mul_f32_e32 v64, v204, v64
	v_fmamk_f32 v163, v207, 0xbdd2d3e7, v175
	v_exp_f32_e32 v64, v64
	v_mul_f32_e32 v163, v205, v163
	v_exp_f32_e32 v163, v163
	v_mov_b64_e32 v[164:165], v[166:167]
	v_add_f32_e32 v64, 1.0, v64
	v_rcp_f32_e32 v206, v64
	v_add_f32_e32 v64, 1.0, v163
	v_rcp_f32_e32 v207, v64
	s_lshl_b32 s22, s22, 7
	v_pk_mul_f32 v[166:167], v[204:205], v[206:207]
	v_pk_mul_f32 v[164:165], v[166:167], v[164:165]
	s_ashr_i32 s23, s22, 31
	v_pk_mul_f32 v[172:173], v[172:173], v[212:213]
	v_cvt_pk_bf16_f32 v221, v164, v165
	v_pk_mul_f32 v[164:165], v[142:143], v[200:201] op_sel_hi:[1,0]
	v_pk_mul_f32 v[142:143], v[138:139], v[200:201] op_sel_hi:[1,0]
	s_lshl_b32 s72, s6, 1
	v_pk_mul_f32 v[172:173], v[172:173], v[208:209]
	v_lshlrev_b32_e32 v64, 1, v184
	v_cvt_pk_bf16_f32 v220, v172, v173
	v_pk_mul_f32 v[144:145], v[144:145], v[200:201] op_sel_hi:[1,0]
	v_pk_mul_f32 v[140:141], v[140:141], v[200:201] op_sel_hi:[1,0]
	v_cndmask_b32_e64 v138, 0, 1, s[26:27]
	v_pk_fma_f32 v[206:207], v[164:165], v[130:131], v[134:135]
	v_fmac_f32_dpp v206, v164, v126 row_shr:1 row_mask:0xf bank_mask:0xf
	v_fmac_f32_dpp v206, v158, v126 row_shl:15 row_mask:0xf bank_mask:0xf
	v_fmac_f32_dpp v206, v164, v122 row_shr:2 row_mask:0xf bank_mask:0xf
	v_fmac_f32_dpp v206, v158, v122 row_shl:14 row_mask:0xf bank_mask:0xf
	v_fmac_f32_dpp v207, v165, v127 row_shr:1 row_mask:0xf bank_mask:0xf
	v_fmac_f32_dpp v207, v159, v127 row_shl:15 row_mask:0xf bank_mask:0xf
	v_fmac_f32_dpp v207, v165, v123 row_shr:2 row_mask:0xf bank_mask:0xf
	v_fmac_f32_dpp v207, v159, v123 row_shl:14 row_mask:0xf bank_mask:0xf
	v_pk_fma_f32 v[158:159], v[144:145], v[132:133], v[136:137]
	v_fmac_f32_dpp v158, v144, v128 row_shr:1 row_mask:0xf bank_mask:0xf
	v_fmac_f32_dpp v158, v160, v128 row_shl:15 row_mask:0xf bank_mask:0xf
	v_fmac_f32_dpp v158, v144, v124 row_shr:2 row_mask:0xf bank_mask:0xf
	v_fmac_f32_dpp v158, v160, v124 row_shl:14 row_mask:0xf bank_mask:0xf
	v_fmac_f32_dpp v159, v145, v129 row_shr:1 row_mask:0xf bank_mask:0xf
	v_fmac_f32_dpp v159, v161, v129 row_shl:15 row_mask:0xf bank_mask:0xf
	v_fmac_f32_dpp v159, v145, v125 row_shr:2 row_mask:0xf bank_mask:0xf
	v_fmac_f32_dpp v159, v161, v125 row_shl:14 row_mask:0xf bank_mask:0xf
	v_pk_fma_f32 v[168:169], v[142:143], v[114:115], v[118:119]
	v_fmac_f32_dpp v168, v142, v106 row_shr:1 row_mask:0xf bank_mask:0xf
	v_fmac_f32_dpp v168, v154, v106 row_shl:15 row_mask:0xf bank_mask:0xf
	v_fmac_f32_dpp v168, v142, v102 row_shr:2 row_mask:0xf bank_mask:0xf
	v_fmac_f32_dpp v168, v154, v102 row_shl:14 row_mask:0xf bank_mask:0xf
	v_fmac_f32_dpp v169, v143, v107 row_shr:1 row_mask:0xf bank_mask:0xf
	v_fmac_f32_dpp v169, v155, v107 row_shl:15 row_mask:0xf bank_mask:0xf
	v_fmac_f32_dpp v169, v143, v103 row_shr:2 row_mask:0xf bank_mask:0xf
	v_fmac_f32_dpp v169, v155, v103 row_shl:14 row_mask:0xf bank_mask:0xf
	v_pk_fma_f32 v[154:155], v[140:141], v[116:117], v[120:121]
	v_fmac_f32_dpp v154, v140, v108 row_shr:1 row_mask:0xf bank_mask:0xf
	v_fmac_f32_dpp v154, v156, v108 row_shl:15 row_mask:0xf bank_mask:0xf
	v_fmac_f32_dpp v154, v140, v104 row_shr:2 row_mask:0xf bank_mask:0xf
	v_fmac_f32_dpp v154, v156, v104 row_shl:14 row_mask:0xf bank_mask:0xf
	v_fmac_f32_dpp v155, v141, v109 row_shr:1 row_mask:0xf bank_mask:0xf
	v_fmac_f32_dpp v155, v157, v109 row_shl:15 row_mask:0xf bank_mask:0xf
	v_fmac_f32_dpp v155, v141, v105 row_shr:2 row_mask:0xf bank_mask:0xf
	v_fmac_f32_dpp v155, v157, v105 row_shl:14 row_mask:0xf bank_mask:0xf
	s_mov_b64 s[30:31], -1
	v_cmp_ne_u32_e64 s[44:45], 1, v138
	s_andn2_b64 vcc, exec, s[26:27]
	v_add_u32_e32 v199, 0xfffff510, v201
	s_cbranch_vccnz .LBB0_263
	s_add_u32 s26, s55, s24
	s_addc_u32 s27, s58, s25
	s_mov_b64 s[30:31], 0

; DI unsigned pk2(float lo, float hi) { f32x2_t v = {lo, hi}; bf16x2_t b = __builtin_convertvector(v, bf16x2_t); return __builtin_bit_cast(unsigned, b); }
; template <int CTRL> DI float dppf(float v) { return __int_as_float(__builtin_amdgcn_mov_dpp(__float_as_int(v), CTRL, 0xf, 0xf, true)); }
;     DI void operator()(pg8::f32x4 (&acc)[2][2][4][2], const pg8::Unit& u, int wr, int wc, int fr, int fq) const {
;     ...
;                 for (int m = 0; m < 4; ++m) {
;                     float cv[2][4];
; #pragma unroll
;                     for (int bj = 0; bj < 2; ++bj) {
;                         const pg8::f32x4 cur = acc[ai][bj][m][n];
;                         pg8::f32x4 prv;
;                         if (m > 0) prv = acc[ai][bj][m > 0 ? m - 1 : 0][n]; else prv = (pg8::f32x4){hal[bj][0], hal[bj][1], hal[bj][2], hal[bj][3]};
; #pragma unroll
;                         for (int i = 0; i < 4; ++i) {
;                             const float q1 = dppf<0x121>(prv[i]), q2 = dppf<0x122>(prv[i]);
;                             const float p1 = __int_as_float(__builtin_amdgcn_update_dpp(__float_as_int(q1), __float_as_int(cur[i]), 0x111, 0xf, 0xf, false));
;                             const float p2 = __int_as_float(__builtin_amdgcn_update_dpp(__float_as_int(q2), __float_as_int(cur[i]), 0x112, 0xf, 0xf, false));
;                             cv[bj][i] = cb[bj][i] + w0[bj][i] * p2 + w1[bj][i] * p1 + w2[bj][i] * cur[i];
;                         }
;                     }
;                     float o[4];
; #pragma unroll
;                     for (int i = 0; i < 4; ++i) o[i] = gelu_tanh(cv[0][i]) * cv[1][i];
;                     const int row = u.pm * 256 + ai * 128 + wr * 64 + m * 16 + fr;
;                     v2u w; w.x = pk2(o[0], o[1]); w.y = pk2(o[2], o[3]);
;                     *(v2u*)(a_row(wsb, row) + u.pn * 128 + wc * 32 + 8 * fq + 4 * n) = w;
.LBB0_265:
	v_mov_b64_e32 v[172:173], v[206:207]
	v_pk_mul_f32 v[206:207], v[172:173], v[172:173]
	v_pk_mul_f32 v[160:161], v[158:159], v[158:159]
	v_fmamk_f32 v139, v206, 0xbdd2d3e7, v175
	v_mul_f32_e32 v139, v172, v139
	v_fmamk_f32 v163, v207, 0xbdd2d3e7, v175
	v_exp_f32_e32 v139, v139
	v_mul_f32_e32 v163, v173, v163
	v_exp_f32_e32 v163, v163
	v_add_f32_e32 v139, 1.0, v139
	v_rcp_f32_e32 v206, v139
	v_add_f32_e32 v139, 1.0, v163
	v_rcp_f32_e32 v207, v139
	v_fmamk_f32 v139, v160, 0xbdd2d3e7, v175
	v_mul_f32_e32 v139, v158, v139
	v_fmamk_f32 v160, v161, 0xbdd2d3e7, v175
	v_exp_f32_e32 v139, v139
	v_mul_f32_e32 v160, v159, v160
	v_exp_f32_e32 v163, v160
	v_pk_mul_f32 v[172:173], v[172:173], v[206:207]
	v_add_f32_e32 v139, 1.0, v139
	v_pk_mul_f32 v[160:161], v[172:173], v[168:169]
	v_rcp_f32_e32 v168, v139
	v_add_f32_e32 v139, 1.0, v163
	v_rcp_f32_e32 v169, v139
	v_pk_mul_f32 v[112:113], v[112:113], v[198:199] op_sel_hi:[1,0]
	v_pk_mul_f32 v[156:157], v[158:159], v[168:169]
	v_pk_mul_f32 v[100:101], v[100:101], v[198:199] op_sel_hi:[1,0]
	v_pk_mul_f32 v[154:155], v[156:157], v[154:155]
	v_cvt_pk_bf16_f32 v222, v160, v161
	v_cvt_pk_bf16_f32 v223, v154, v155
	v_pk_mul_f32 v[154:155], v[110:111], v[198:199] op_sel_hi:[1,0]
	v_pk_mul_f32 v[98:99], v[98:99], v[198:199] op_sel_hi:[1,0]
	v_pk_fma_f32 v[166:167], v[154:155], v[130:131], v[134:135]
	v_fmac_f32_dpp v166, v154, v126 row_shr:1 row_mask:0xf bank_mask:0xf
	v_fmac_f32_dpp v166, v164, v126 row_shl:15 row_mask:0xf bank_mask:0xf
	v_fmac_f32_dpp v166, v154, v122 row_shr:2 row_mask:0xf bank_mask:0xf
	v_fmac_f32_dpp v166, v164, v122 row_shl:14 row_mask:0xf bank_mask:0xf
	v_fmac_f32_dpp v167, v155, v127 row_shr:1 row_mask:0xf bank_mask:0xf
	v_fmac_f32_dpp v167, v165, v127 row_shl:15 row_mask:0xf bank_mask:0xf
	v_fmac_f32_dpp v167, v155, v123 row_shr:2 row_mask:0xf bank_mask:0xf
	v_fmac_f32_dpp v167, v165, v123 row_shl:14 row_mask:0xf bank_mask:0xf
	v_pk_fma_f32 v[156:157], v[112:113], v[132:133], v[136:137]
	v_fmac_f32_dpp v156, v112, v128 row_shr:1 row_mask:0xf bank_mask:0xf
	v_fmac_f32_dpp v156, v144, v128 row_shl:15 row_mask:0xf bank_mask:0xf
	v_fmac_f32_dpp v156, v112, v124 row_shr:2 row_mask:0xf bank_mask:0xf
	v_fmac_f32_dpp v156, v144, v124 row_shl:14 row_mask:0xf bank_mask:0xf
	v_fmac_f32_dpp v157, v113, v129 row_shr:1 row_mask:0xf bank_mask:0xf
	v_fmac_f32_dpp v157, v145, v129 row_shl:15 row_mask:0xf bank_mask:0xf
	v_fmac_f32_dpp v157, v113, v125 row_shr:2 row_mask:0xf bank_mask:0xf
	v_fmac_f32_dpp v157, v145, v125 row_shl:14 row_mask:0xf bank_mask:0xf
	v_pk_fma_f32 v[160:161], v[98:99], v[114:115], v[118:119]
	v_fmac_f32_dpp v160, v98, v106 row_shr:1 row_mask:0xf bank_mask:0xf
	v_fmac_f32_dpp v160, v142, v106 row_shl:15 row_mask:0xf bank_mask:0xf
	v_fmac_f32_dpp v160, v98, v102 row_shr:2 row_mask:0xf bank_mask:0xf
	v_fmac_f32_dpp v160, v142, v102 row_shl:14 row_mask:0xf bank_mask:0xf
	v_fmac_f32_dpp v161, v99, v107 row_shr:1 row_mask:0xf bank_mask:0xf
	v_fmac_f32_dpp v161, v143, v107 row_shl:15 row_mask:0xf bank_mask:0xf
	v_fmac_f32_dpp v161, v99, v103 row_shr:2 row_mask:0xf bank_mask:0xf
	v_fmac_f32_dpp v161, v143, v103 row_shl:14 row_mask:0xf bank_mask:0xf
	v_pk_fma_f32 v[142:143], v[100:101], v[116:117], v[120:121]
	v_fmac_f32_dpp v142, v100, v108 row_shr:1 row_mask:0xf bank_mask:0xf
	v_fmac_f32_dpp v142, v140, v108 row_shl:15 row_mask:0xf bank_mask:0xf
	v_fmac_f32_dpp v142, v100, v104 row_shr:2 row_mask:0xf bank_mask:0xf
	v_fmac_f32_dpp v142, v140, v104 row_shl:14 row_mask:0xf bank_mask:0xf
	v_fmac_f32_dpp v143, v101, v109 row_shr:1 row_mask:0xf bank_mask:0xf
	v_fmac_f32_dpp v143, v141, v109 row_shl:15 row_mask:0xf bank_mask:0xf
	v_fmac_f32_dpp v143, v101, v105 row_shr:2 row_mask:0xf bank_mask:0xf
	v_fmac_f32_dpp v143, v141, v105 row_shl:14 row_mask:0xf bank_mask:0xf
	s_mov_b64 s[26:27], -1
	s_and_b64 vcc, exec, s[44:45]
	v_add_u32_e32 v197, 0xfffff520, v201
	s_cbranch_vccnz .LBB0_267
	s_add_u32 s26, s55, s24
	s_addc_u32 s27, s58, s25
	s_mov_b64 s[26:27], 0

; DI unsigned pk2(float lo, float hi) { f32x2_t v = {lo, hi}; bf16x2_t b = __builtin_convertvector(v, bf16x2_t); return __builtin_bit_cast(unsigned, b); }
; template <int CTRL> DI float dppf(float v) { return __int_as_float(__builtin_amdgcn_mov_dpp(__float_as_int(v), CTRL, 0xf, 0xf, true)); }
;     DI void operator()(pg8::f32x4 (&acc)[2][2][4][2], const pg8::Unit& u, int wr, int wc, int fr, int fq) const {
;     ...
;                 for (int m = 0; m < 4; ++m) {
;                     float cv[2][4];
; #pragma unroll
;                     for (int bj = 0; bj < 2; ++bj) {
;                         const pg8::f32x4 cur = acc[ai][bj][m][n];
;                         pg8::f32x4 prv;
;                         if (m > 0) prv = acc[ai][bj][m > 0 ? m - 1 : 0][n]; else prv = (pg8::f32x4){hal[bj][0], hal[bj][1], hal[bj][2], hal[bj][3]};
; #pragma unroll
;                         for (int i = 0; i < 4; ++i) {
;                             const float q1 = dppf<0x121>(prv[i]), q2 = dppf<0x122>(prv[i]);
;                             const float p1 = __int_as_float(__builtin_amdgcn_update_dpp(__float_as_int(q1), __float_as_int(cur[i]), 0x111, 0xf, 0xf, false));
;                             const float p2 = __int_as_float(__builtin_amdgcn_update_dpp(__float_as_int(q2), __float_as_int(cur[i]), 0x112, 0xf, 0xf, false));
;                             cv[bj][i] = cb[bj][i] + w0[bj][i] * p2 + w1[bj][i] * p1 + w2[bj][i] * cur[i];
;                         }
;                     }
;                     float o[4];
; #pragma unroll
;                     for (int i = 0; i < 4; ++i) o[i] = gelu_tanh(cv[0][i]) * cv[1][i];
;                     const int row = u.pm * 256 + ai * 128 + wr * 64 + m * 16 + fr;
;                     v2u w; w.x = pk2(o[0], o[1]); w.y = pk2(o[2], o[3]);
;                     *(v2u*)(a_row(wsb, row) + u.pn * 128 + wc * 32 + 8 * fq + 4 * n) = w;
.LBB0_269:
	v_mov_b64_e32 v[144:145], v[156:157]
	v_pk_mul_f32 v[168:169], v[166:167], v[166:167]
	v_pk_mul_f32 v[156:157], v[144:145], v[144:145]
	v_fmamk_f32 v111, v168, 0xbdd2d3e7, v175
	v_mul_f32_e32 v111, v166, v111
	v_fmamk_f32 v139, v169, 0xbdd2d3e7, v175
	v_exp_f32_e32 v111, v111
	v_mul_f32_e32 v139, v167, v139
	v_exp_f32_e32 v139, v139
	v_add_f32_e32 v111, 1.0, v111
	v_rcp_f32_e32 v168, v111
	v_add_f32_e32 v111, 1.0, v139
	v_rcp_f32_e32 v169, v111
	v_fmamk_f32 v111, v156, 0xbdd2d3e7, v175
	v_mul_f32_e32 v111, v144, v111
	v_fmamk_f32 v139, v157, 0xbdd2d3e7, v175
	v_exp_f32_e32 v111, v111
	v_mul_f32_e32 v139, v145, v139
	v_exp_f32_e32 v139, v139
	v_pk_mul_f32 v[164:165], v[166:167], v[168:169]
	v_add_f32_e32 v111, 1.0, v111
	v_pk_mul_f32 v[156:157], v[164:165], v[160:161]
	v_rcp_f32_e32 v160, v111
	v_add_f32_e32 v111, 1.0, v139
	v_rcp_f32_e32 v161, v111
	s_mov_b64 s[26:27], -1
	v_mov_b64_e32 v[140:141], v[142:143]
	v_pk_mul_f32 v[142:143], v[144:145], v[160:161]
	v_pk_mul_f32 v[140:141], v[142:143], v[140:141]
	v_cvt_pk_bf16_f32 v224, v156, v157
	v_cvt_pk_bf16_f32 v225, v140, v141
	v_pk_fma_f32 v[158:159], v[150:151], v[130:131], v[134:135]
	v_fmac_f32_dpp v158, v150, v126 row_shr:1 row_mask:0xf bank_mask:0xf
	v_fmac_f32_dpp v158, v154, v126 row_shl:15 row_mask:0xf bank_mask:0xf
	v_fmac_f32_dpp v158, v150, v122 row_shr:2 row_mask:0xf bank_mask:0xf
	v_fmac_f32_dpp v158, v154, v122 row_shl:14 row_mask:0xf bank_mask:0xf
	v_fmac_f32_dpp v159, v151, v127 row_shr:1 row_mask:0xf bank_mask:0xf
	v_fmac_f32_dpp v159, v155, v127 row_shl:15 row_mask:0xf bank_mask:0xf
	v_fmac_f32_dpp v159, v151, v123 row_shr:2 row_mask:0xf bank_mask:0xf
	v_fmac_f32_dpp v159, v155, v123 row_shl:14 row_mask:0xf bank_mask:0xf
	v_pk_fma_f32 v[140:141], v[152:153], v[132:133], v[136:137]
	v_fmac_f32_dpp v140, v152, v128 row_shr:1 row_mask:0xf bank_mask:0xf
	v_fmac_f32_dpp v140, v112, v128 row_shl:15 row_mask:0xf bank_mask:0xf
	v_fmac_f32_dpp v140, v152, v124 row_shr:2 row_mask:0xf bank_mask:0xf
	v_fmac_f32_dpp v140, v112, v124 row_shl:14 row_mask:0xf bank_mask:0xf
	v_fmac_f32_dpp v141, v153, v129 row_shr:1 row_mask:0xf bank_mask:0xf
	v_fmac_f32_dpp v141, v113, v129 row_shl:15 row_mask:0xf bank_mask:0xf
	v_fmac_f32_dpp v141, v153, v125 row_shr:2 row_mask:0xf bank_mask:0xf
	v_fmac_f32_dpp v141, v113, v125 row_shl:14 row_mask:0xf bank_mask:0xf
	v_pk_fma_f32 v[154:155], v[146:147], v[114:115], v[118:119]
	v_fmac_f32_dpp v154, v146, v106 row_shr:1 row_mask:0xf bank_mask:0xf
	v_fmac_f32_dpp v154, v98, v106 row_shl:15 row_mask:0xf bank_mask:0xf
	v_fmac_f32_dpp v154, v146, v102 row_shr:2 row_mask:0xf bank_mask:0xf
	v_fmac_f32_dpp v154, v98, v102 row_shl:14 row_mask:0xf bank_mask:0xf
	v_fmac_f32_dpp v155, v147, v107 row_shr:1 row_mask:0xf bank_mask:0xf
	v_fmac_f32_dpp v155, v99, v107 row_shl:15 row_mask:0xf bank_mask:0xf
	v_fmac_f32_dpp v155, v147, v103 row_shr:2 row_mask:0xf bank_mask:0xf
	v_fmac_f32_dpp v155, v99, v103 row_shl:14 row_mask:0xf bank_mask:0xf
	v_pk_fma_f32 v[98:99], v[148:149], v[116:117], v[120:121]
	v_fmac_f32_dpp v98, v148, v108 row_shr:1 row_mask:0xf bank_mask:0xf
	v_fmac_f32_dpp v98, v100, v108 row_shl:15 row_mask:0xf bank_mask:0xf
	v_fmac_f32_dpp v98, v148, v104 row_shr:2 row_mask:0xf bank_mask:0xf
	v_fmac_f32_dpp v98, v100, v104 row_shl:14 row_mask:0xf bank_mask:0xf
	v_fmac_f32_dpp v99, v149, v109 row_shr:1 row_mask:0xf bank_mask:0xf
	v_fmac_f32_dpp v99, v101, v109 row_shl:15 row_mask:0xf bank_mask:0xf
	v_fmac_f32_dpp v99, v149, v105 row_shr:2 row_mask:0xf bank_mask:0xf
	v_fmac_f32_dpp v99, v101, v105 row_shl:14 row_mask:0xf bank_mask:0xf
	s_and_b64 vcc, exec, s[44:45]
	v_add_u32_e32 v164, 0xfffff530, v201
	s_cbranch_vccnz .LBB0_271
	s_add_u32 s26, s55, s24
	s_addc_u32 s27, s58, s25
	s_mov_b64 s[26:27], 0

; DI unsigned pk2(float lo, float hi) { f32x2_t v = {lo, hi}; bf16x2_t b = __builtin_convertvector(v, bf16x2_t); return __builtin_bit_cast(unsigned, b); }
; template <int CTRL> DI float dppf(float v) { return __int_as_float(__builtin_amdgcn_mov_dpp(__float_as_int(v), CTRL, 0xf, 0xf, true)); }
;     DI void operator()(pg8::f32x4 (&acc)[2][2][4][2], const pg8::Unit& u, int wr, int wc, int fr, int fq) const {
;     ...
;             for (int ai = 0; ai < 2; ++ai) {
;                 v4f hal[2];
;                 {
;                     const bool has = (wr == 1) || (ai == 1);
;                     const int as = (wr == 1) ? ai : 0, ws_ = (wr == 1) ? 0 : 1;
; #pragma unroll
;                     for (int bj = 0; bj < 2; ++bj) { v4f hv = H[(((as * 2 + ws_) * 4 + wc) * 4 + bj * 2 + n) * 8 + hl]; hal[bj] = has ? hv : (v4f){0.f, 0.f, 0.f, 0.f}; }
;                 }
; #pragma unroll
;                 for (int m = 0; m < 4; ++m) {
;                     float cv[2][4];
; #pragma unroll
;                     for (int bj = 0; bj < 2; ++bj) {
;                         const pg8::f32x4 cur = acc[ai][bj][m][n];
;                         pg8::f32x4 prv;
;                         if (m > 0) prv = acc[ai][bj][m > 0 ? m - 1 : 0][n]; else prv = (pg8::f32x4){hal[bj][0], hal[bj][1], hal[bj][2], hal[bj][3]};
; #pragma unroll
;                         for (int i = 0; i < 4; ++i) {
;                             const float q1 = dppf<0x121>(prv[i]), q2 = dppf<0x122>(prv[i]);
;                             const float p1 = __int_as_float(__builtin_amdgcn_update_dpp(__float_as_int(q1), __float_as_int(cur[i]), 0x111, 0xf, 0xf, false));
;                             const float p2 = __int_as_float(__builtin_amdgcn_update_dpp(__float_as_int(q2), __float_as_int(cur[i]), 0x112, 0xf, 0xf, false));
;                             cv[bj][i] = cb[bj][i] + w0[bj][i] * p2 + w1[bj][i] * p1 + w2[bj][i] * cur[i];
;                         }
;                     }
;                     float o[4];
; #pragma unroll
;                     for (int i = 0; i < 4; ++i) o[i] = gelu_tanh(cv[0][i]) * cv[1][i];
;                     const int row = u.pm * 256 + ai * 128 + wr * 64 + m * 16 + fr;
;                     v2u w; w.x = pk2(o[0], o[1]); w.y = pk2(o[2], o[3]);
;                     *(v2u*)(a_row(wsb, row) + u.pn * 128 + wc * 32 + 8 * fq + 4 * n) = w;
.LBB0_273:
	v_mov_b64_e32 v[150:151], v[158:159]
	v_pk_mul_f32 v[158:159], v[150:151], v[150:151]
	v_pk_mul_f32 v[142:143], v[140:141], v[140:141]
	v_fmamk_f32 v111, v158, 0xbdd2d3e7, v175
	v_mul_f32_e32 v111, v150, v111
	v_fmamk_f32 v113, v159, 0xbdd2d3e7, v175
	v_exp_f32_e32 v111, v111
	v_mul_f32_e32 v113, v151, v113
	v_exp_f32_e32 v113, v113
	v_add_f32_e32 v111, 1.0, v111
	v_rcp_f32_e32 v158, v111
	v_add_f32_e32 v111, 1.0, v113
	v_rcp_f32_e32 v159, v111
	v_fmamk_f32 v111, v142, 0xbdd2d3e7, v175
	v_mul_f32_e32 v111, v140, v111
	v_fmamk_f32 v113, v143, 0xbdd2d3e7, v175
	v_exp_f32_e32 v111, v111
	v_mul_f32_e32 v113, v141, v113
	v_exp_f32_e32 v113, v113
	v_pk_mul_f32 v[150:151], v[150:151], v[158:159]
	v_mov_b64_e32 v[146:147], v[154:155]
	v_add_f32_e32 v111, 1.0, v111
	v_pk_mul_f32 v[142:143], v[150:151], v[146:147]
	v_rcp_f32_e32 v146, v111
	v_add_f32_e32 v111, 1.0, v113
	v_rcp_f32_e32 v147, v111
	s_addk_i32 s34, 0x80
	v_pk_mul_f32 v[100:101], v[140:141], v[146:147]
	s_ashr_i32 s30, s34, 12
	v_pk_mul_f32 v[98:99], v[100:101], v[98:99]
	v_cvt_pk_bf16_f32 v232, v142, v143
	v_cvt_pk_bf16_f32 v233, v98, v99
	ds_read_b128 v[140:143], v218
	ds_read_b128 v[144:147], v218 offset:256
	s_ashr_i32 s31, s30, 31
	s_and_b32 s49, s34, 0xfc0
	s_lshl_b64 s[26:27], s[30:31], 23
	v_pk_mul_f32 v[84:85], v[84:85], v[196:197] op_sel_hi:[1,0]
	v_pk_mul_f32 v[82:83], v[82:83], v[196:197] op_sel_hi:[1,0]
	v_pk_mul_f32 v[76:77], v[76:77], v[196:197] op_sel_hi:[1,0]
	v_pk_mul_f32 v[74:75], v[74:75], v[196:197] op_sel_hi:[1,0]
	s_waitcnt lgkmcnt(1)
	s_waitcnt lgkmcnt(0)
	v_or_b32_e32 v111, s49, v170
	s_cmpk_gt_u32 s49, 0xaff
	v_pk_fma_f32 v[152:153], v[82:83], v[130:131], v[134:135]
	v_fmac_f32_dpp v152, v82, v126 row_shr:1 row_mask:0xf bank_mask:0xf
	v_fmac_f32_dpp v152, v140, v126 row_shl:15 row_mask:0xf bank_mask:0xf
	v_fmac_f32_dpp v152, v82, v122 row_shr:2 row_mask:0xf bank_mask:0xf
	v_fmac_f32_dpp v152, v140, v122 row_shl:14 row_mask:0xf bank_mask:0xf
	v_fmac_f32_dpp v153, v83, v127 row_shr:1 row_mask:0xf bank_mask:0xf
	v_fmac_f32_dpp v153, v141, v127 row_shl:15 row_mask:0xf bank_mask:0xf
	v_fmac_f32_dpp v153, v83, v123 row_shr:2 row_mask:0xf bank_mask:0xf
	v_fmac_f32_dpp v153, v141, v123 row_shl:14 row_mask:0xf bank_mask:0xf
	v_pk_fma_f32 v[100:101], v[84:85], v[132:133], v[136:137]
	v_fmac_f32_dpp v100, v84, v128 row_shr:1 row_mask:0xf bank_mask:0xf
	v_fmac_f32_dpp v100, v142, v128 row_shl:15 row_mask:0xf bank_mask:0xf
	v_fmac_f32_dpp v100, v84, v124 row_shr:2 row_mask:0xf bank_mask:0xf
	v_fmac_f32_dpp v100, v142, v124 row_shl:14 row_mask:0xf bank_mask:0xf
	v_fmac_f32_dpp v101, v85, v129 row_shr:1 row_mask:0xf bank_mask:0xf
	v_fmac_f32_dpp v101, v143, v129 row_shl:15 row_mask:0xf bank_mask:0xf
	v_fmac_f32_dpp v101, v85, v125 row_shr:2 row_mask:0xf bank_mask:0xf
	v_fmac_f32_dpp v101, v143, v125 row_shl:14 row_mask:0xf bank_mask:0xf
	v_pk_fma_f32 v[148:149], v[74:75], v[114:115], v[118:119]
	v_fmac_f32_dpp v148, v74, v106 row_shr:1 row_mask:0xf bank_mask:0xf
	v_fmac_f32_dpp v148, v144, v106 row_shl:15 row_mask:0xf bank_mask:0xf
	v_fmac_f32_dpp v148, v74, v102 row_shr:2 row_mask:0xf bank_mask:0xf
	v_fmac_f32_dpp v148, v144, v102 row_shl:14 row_mask:0xf bank_mask:0xf
	v_fmac_f32_dpp v149, v75, v107 row_shr:1 row_mask:0xf bank_mask:0xf
	v_fmac_f32_dpp v149, v145, v107 row_shl:15 row_mask:0xf bank_mask:0xf
	v_fmac_f32_dpp v149, v75, v103 row_shr:2 row_mask:0xf bank_mask:0xf
	v_fmac_f32_dpp v149, v145, v103 row_shl:14 row_mask:0xf bank_mask:0xf
	v_pk_fma_f32 v[98:99], v[76:77], v[116:117], v[120:121]
	v_fmac_f32_dpp v98, v76, v108 row_shr:1 row_mask:0xf bank_mask:0xf
	v_fmac_f32_dpp v98, v146, v108 row_shl:15 row_mask:0xf bank_mask:0xf
	v_fmac_f32_dpp v98, v76, v104 row_shr:2 row_mask:0xf bank_mask:0xf
	v_fmac_f32_dpp v98, v146, v104 row_shl:14 row_mask:0xf bank_mask:0xf
	v_fmac_f32_dpp v99, v77, v109 row_shr:1 row_mask:0xf bank_mask:0xf
	v_fmac_f32_dpp v99, v147, v109 row_shl:15 row_mask:0xf bank_mask:0xf
	v_fmac_f32_dpp v99, v77, v105 row_shr:2 row_mask:0xf bank_mask:0xf
	v_fmac_f32_dpp v99, v147, v105 row_shl:14 row_mask:0xf bank_mask:0xf
	s_mov_b64 s[46:47], -1
	s_cselect_b64 s[34:35], -1, 0
	s_cmpk_lt_u32 s49, 0xb00
	v_add_u32_e32 v156, 0xfffff500, v111
	s_cbranch_scc1 .LBB0_275
	s_add_u32 s46, s55, s26
	s_addc_u32 s47, s58, s27
	v_mov_b64_e32 v[144:145], s[46:47]
	v_mad_u64_u32 v[144:145], s[46:47], v156, s0, v[144:145]
	s_mov_b64 s[46:47], 0

; DI unsigned pk2(float lo, float hi) { f32x2_t v = {lo, hi}; bf16x2_t b = __builtin_convertvector(v, bf16x2_t); return __builtin_bit_cast(unsigned, b); }
; template <int CTRL> DI float dppf(float v) { return __int_as_float(__builtin_amdgcn_mov_dpp(__float_as_int(v), CTRL, 0xf, 0xf, true)); }
;     DI void operator()(pg8::f32x4 (&acc)[2][2][4][2], const pg8::Unit& u, int wr, int wc, int fr, int fq) const {
;     ...
;                 for (int m = 0; m < 4; ++m) {
;                     float cv[2][4];
; #pragma unroll
;                     for (int bj = 0; bj < 2; ++bj) {
;                         const pg8::f32x4 cur = acc[ai][bj][m][n];
;                         pg8::f32x4 prv;
;                         if (m > 0) prv = acc[ai][bj][m > 0 ? m - 1 : 0][n]; else prv = (pg8::f32x4){hal[bj][0], hal[bj][1], hal[bj][2], hal[bj][3]};
; #pragma unroll
;                         for (int i = 0; i < 4; ++i) {
;                             const float q1 = dppf<0x121>(prv[i]), q2 = dppf<0x122>(prv[i]);
;                             const float p1 = __int_as_float(__builtin_amdgcn_update_dpp(__float_as_int(q1), __float_as_int(cur[i]), 0x111, 0xf, 0xf, false));
;                             const float p2 = __int_as_float(__builtin_amdgcn_update_dpp(__float_as_int(q2), __float_as_int(cur[i]), 0x112, 0xf, 0xf, false));
;                             cv[bj][i] = cb[bj][i] + w0[bj][i] * p2 + w1[bj][i] * p1 + w2[bj][i] * cur[i];
;                         }
;                     }
;                     float o[4];
; #pragma unroll
;                     for (int i = 0; i < 4; ++i) o[i] = gelu_tanh(cv[0][i]) * cv[1][i];
;                     const int row = u.pm * 256 + ai * 128 + wr * 64 + m * 16 + fr;
;                     v2u w; w.x = pk2(o[0], o[1]); w.y = pk2(o[2], o[3]);
;                     *(v2u*)(a_row(wsb, row) + u.pn * 128 + wc * 32 + 8 * fq + 4 * n) = w;
.LBB0_277:
	v_pk_mul_f32 v[154:155], v[152:153], v[152:153]
	v_pk_mul_f32 v[142:143], v[100:101], v[100:101]
	v_fmamk_f32 v113, v154, 0xbdd2d3e7, v175
	v_mul_f32_e32 v113, v152, v113
	v_fmamk_f32 v139, v155, 0xbdd2d3e7, v175
	v_exp_f32_e32 v113, v113
	v_mul_f32_e32 v139, v153, v139
	v_exp_f32_e32 v139, v139
	v_add_f32_e32 v113, 1.0, v113
	v_rcp_f32_e32 v154, v113
	v_add_f32_e32 v113, 1.0, v139
	v_rcp_f32_e32 v155, v113
	v_fmamk_f32 v113, v142, 0xbdd2d3e7, v175
	v_mul_f32_e32 v113, v100, v113
	v_fmamk_f32 v139, v143, 0xbdd2d3e7, v175
	v_exp_f32_e32 v113, v113
	v_mul_f32_e32 v139, v101, v139
	v_exp_f32_e32 v139, v139
	v_pk_mul_f32 v[150:151], v[152:153], v[154:155]
	v_add_f32_e32 v113, 1.0, v113
	v_pk_mul_f32 v[142:143], v[150:151], v[148:149]
	v_rcp_f32_e32 v148, v113
	v_add_f32_e32 v113, 1.0, v139
	v_rcp_f32_e32 v149, v113
	v_pk_mul_f32 v[72:73], v[72:73], v[194:195] op_sel_hi:[1,0]
	v_pk_mul_f32 v[100:101], v[100:101], v[148:149]
	v_pk_mul_f32 v[70:71], v[70:71], v[194:195] op_sel_hi:[1,0]
	v_pk_mul_f32 v[98:99], v[100:101], v[98:99]
	v_cvt_pk_bf16_f32 v238, v142, v143
	v_cvt_pk_bf16_f32 v239, v98, v99
	v_pk_mul_f32 v[68:69], v[68:69], v[194:195] op_sel_hi:[1,0]
	v_pk_mul_f32 v[66:67], v[66:67], v[194:195] op_sel_hi:[1,0]
	v_cndmask_b32_e64 v98, 0, 1, s[34:35]
	v_pk_fma_f32 v[142:143], v[70:71], v[130:131], v[134:135]
	v_fmac_f32_dpp v142, v70, v126 row_shr:1 row_mask:0xf bank_mask:0xf
	v_fmac_f32_dpp v142, v82, v126 row_shl:15 row_mask:0xf bank_mask:0xf
	v_fmac_f32_dpp v142, v70, v122 row_shr:2 row_mask:0xf bank_mask:0xf
	v_fmac_f32_dpp v142, v82, v122 row_shl:14 row_mask:0xf bank_mask:0xf
	v_fmac_f32_dpp v143, v71, v127 row_shr:1 row_mask:0xf bank_mask:0xf
	v_fmac_f32_dpp v143, v83, v127 row_shl:15 row_mask:0xf bank_mask:0xf
	v_fmac_f32_dpp v143, v71, v123 row_shr:2 row_mask:0xf bank_mask:0xf
	v_fmac_f32_dpp v143, v83, v123 row_shl:14 row_mask:0xf bank_mask:0xf
	v_pk_fma_f32 v[82:83], v[72:73], v[132:133], v[136:137]
	v_fmac_f32_dpp v82, v72, v128 row_shr:1 row_mask:0xf bank_mask:0xf
	v_fmac_f32_dpp v82, v84, v128 row_shl:15 row_mask:0xf bank_mask:0xf
	v_fmac_f32_dpp v82, v72, v124 row_shr:2 row_mask:0xf bank_mask:0xf
	v_fmac_f32_dpp v82, v84, v124 row_shl:14 row_mask:0xf bank_mask:0xf
	v_fmac_f32_dpp v83, v73, v129 row_shr:1 row_mask:0xf bank_mask:0xf
	v_fmac_f32_dpp v83, v85, v129 row_shl:15 row_mask:0xf bank_mask:0xf
	v_fmac_f32_dpp v83, v73, v125 row_shr:2 row_mask:0xf bank_mask:0xf
	v_fmac_f32_dpp v83, v85, v125 row_shl:14 row_mask:0xf bank_mask:0xf
	v_pk_fma_f32 v[100:101], v[66:67], v[114:115], v[118:119]
	v_fmac_f32_dpp v100, v66, v106 row_shr:1 row_mask:0xf bank_mask:0xf
	v_fmac_f32_dpp v100, v74, v106 row_shl:15 row_mask:0xf bank_mask:0xf
	v_fmac_f32_dpp v100, v66, v102 row_shr:2 row_mask:0xf bank_mask:0xf
	v_fmac_f32_dpp v100, v74, v102 row_shl:14 row_mask:0xf bank_mask:0xf
	v_fmac_f32_dpp v101, v67, v107 row_shr:1 row_mask:0xf bank_mask:0xf
	v_fmac_f32_dpp v101, v75, v107 row_shl:15 row_mask:0xf bank_mask:0xf
	v_fmac_f32_dpp v101, v67, v103 row_shr:2 row_mask:0xf bank_mask:0xf
	v_fmac_f32_dpp v101, v75, v103 row_shl:14 row_mask:0xf bank_mask:0xf
	v_pk_fma_f32 v[74:75], v[68:69], v[116:117], v[120:121]
	v_fmac_f32_dpp v74, v68, v108 row_shr:1 row_mask:0xf bank_mask:0xf
	v_fmac_f32_dpp v74, v76, v108 row_shl:15 row_mask:0xf bank_mask:0xf
	v_fmac_f32_dpp v74, v68, v104 row_shr:2 row_mask:0xf bank_mask:0xf
	v_fmac_f32_dpp v74, v76, v104 row_shl:14 row_mask:0xf bank_mask:0xf
	v_fmac_f32_dpp v75, v69, v109 row_shr:1 row_mask:0xf bank_mask:0xf
	v_fmac_f32_dpp v75, v77, v109 row_shl:15 row_mask:0xf bank_mask:0xf
	v_fmac_f32_dpp v75, v69, v105 row_shr:2 row_mask:0xf bank_mask:0xf
	v_fmac_f32_dpp v75, v77, v105 row_shl:14 row_mask:0xf bank_mask:0xf
	s_mov_b64 s[74:75], -1
	v_cmp_ne_u32_e64 s[46:47], 1, v98
	s_andn2_b64 vcc, exec, s[34:35]
	v_add_u32_e32 v150, 0xfffff510, v111
	s_cbranch_vccnz .LBB0_279
	s_add_u32 s34, s55, s26
	s_addc_u32 s35, s58, s27
	s_mov_b64 s[74:75], 0

; DI unsigned pk2(float lo, float hi) { f32x2_t v = {lo, hi}; bf16x2_t b = __builtin_convertvector(v, bf16x2_t); return __builtin_bit_cast(unsigned, b); }
; template <int CTRL> DI float dppf(float v) { return __int_as_float(__builtin_amdgcn_mov_dpp(__float_as_int(v), CTRL, 0xf, 0xf, true)); }
;     DI void operator()(pg8::f32x4 (&acc)[2][2][4][2], const pg8::Unit& u, int wr, int wc, int fr, int fq) const {
;     ...
;                 for (int m = 0; m < 4; ++m) {
;                     float cv[2][4];
; #pragma unroll
;                     for (int bj = 0; bj < 2; ++bj) {
;                         const pg8::f32x4 cur = acc[ai][bj][m][n];
;                         pg8::f32x4 prv;
;                         if (m > 0) prv = acc[ai][bj][m > 0 ? m - 1 : 0][n]; else prv = (pg8::f32x4){hal[bj][0], hal[bj][1], hal[bj][2], hal[bj][3]};
; #pragma unroll
;                         for (int i = 0; i < 4; ++i) {
;                             const float q1 = dppf<0x121>(prv[i]), q2 = dppf<0x122>(prv[i]);
;                             const float p1 = __int_as_float(__builtin_amdgcn_update_dpp(__float_as_int(q1), __float_as_int(cur[i]), 0x111, 0xf, 0xf, false));
;                             const float p2 = __int_as_float(__builtin_amdgcn_update_dpp(__float_as_int(q2), __float_as_int(cur[i]), 0x112, 0xf, 0xf, false));
;                             cv[bj][i] = cb[bj][i] + w0[bj][i] * p2 + w1[bj][i] * p1 + w2[bj][i] * cur[i];
;                         }
;                     }
;                     float o[4];
; #pragma unroll
;                     for (int i = 0; i < 4; ++i) o[i] = gelu_tanh(cv[0][i]) * cv[1][i];
;                     const int row = u.pm * 256 + ai * 128 + wr * 64 + m * 16 + fr;
;                     v2u w; w.x = pk2(o[0], o[1]); w.y = pk2(o[2], o[3]);
;                     *(v2u*)(a_row(wsb, row) + u.pn * 128 + wc * 32 + 8 * fq + 4 * n) = w;
.LBB0_281:
	v_pk_mul_f32 v[148:149], v[142:143], v[142:143]
	v_pk_mul_f32 v[84:85], v[82:83], v[82:83]
	v_fmamk_f32 v113, v148, 0xbdd2d3e7, v175
	v_mul_f32_e32 v113, v142, v113
	v_fmamk_f32 v139, v149, 0xbdd2d3e7, v175
	v_exp_f32_e32 v113, v113
	v_mul_f32_e32 v139, v143, v139
	v_exp_f32_e32 v139, v139
	v_fmamk_f32 v84, v84, 0xbdd2d3e7, v175
	v_add_f32_e32 v113, 1.0, v113
	v_rcp_f32_e32 v148, v113
	v_add_f32_e32 v113, 1.0, v139
	v_mul_f32_e32 v84, v82, v84
	v_rcp_f32_e32 v149, v113
	v_exp_f32_e32 v113, v84
	v_fmamk_f32 v84, v85, 0xbdd2d3e7, v175
	v_mul_f32_e32 v84, v83, v84
	v_exp_f32_e32 v139, v84
	v_pk_mul_f32 v[140:141], v[142:143], v[148:149]
	v_pk_mul_f32 v[84:85], v[140:141], v[100:101]
	v_add_f32_e32 v100, 1.0, v113
	v_add_f32_e32 v101, 1.0, v139
	v_rcp_f32_e32 v100, v100
	v_rcp_f32_e32 v101, v101
	v_pk_mul_f32 v[62:63], v[62:63], v[192:193] op_sel_hi:[1,0]
	v_pk_mul_f32 v[60:61], v[60:61], v[192:193] op_sel_hi:[1,0]
	v_pk_mul_f32 v[76:77], v[82:83], v[100:101]
	v_pk_mul_f32 v[58:59], v[58:59], v[192:193] op_sel_hi:[1,0]
	v_pk_mul_f32 v[74:75], v[76:77], v[74:75]
	v_cvt_pk_bf16_f32 v242, v84, v85
	v_cvt_pk_bf16_f32 v243, v74, v75
	v_pk_mul_f32 v[56:57], v[56:57], v[192:193] op_sel_hi:[1,0]
	v_pk_fma_f32 v[84:85], v[60:61], v[130:131], v[134:135]
	v_fmac_f32_dpp v84, v60, v126 row_shr:1 row_mask:0xf bank_mask:0xf
	v_fmac_f32_dpp v84, v70, v126 row_shl:15 row_mask:0xf bank_mask:0xf
	v_fmac_f32_dpp v84, v60, v122 row_shr:2 row_mask:0xf bank_mask:0xf
	v_fmac_f32_dpp v84, v70, v122 row_shl:14 row_mask:0xf bank_mask:0xf
	v_fmac_f32_dpp v85, v61, v127 row_shr:1 row_mask:0xf bank_mask:0xf
	v_fmac_f32_dpp v85, v71, v127 row_shl:15 row_mask:0xf bank_mask:0xf
	v_fmac_f32_dpp v85, v61, v123 row_shr:2 row_mask:0xf bank_mask:0xf
	v_fmac_f32_dpp v85, v71, v123 row_shl:14 row_mask:0xf bank_mask:0xf
	v_pk_fma_f32 v[70:71], v[62:63], v[132:133], v[136:137]
	v_fmac_f32_dpp v70, v62, v128 row_shr:1 row_mask:0xf bank_mask:0xf
	v_fmac_f32_dpp v70, v72, v128 row_shl:15 row_mask:0xf bank_mask:0xf
	v_fmac_f32_dpp v70, v62, v124 row_shr:2 row_mask:0xf bank_mask:0xf
	v_fmac_f32_dpp v70, v72, v124 row_shl:14 row_mask:0xf bank_mask:0xf
	v_fmac_f32_dpp v71, v63, v129 row_shr:1 row_mask:0xf bank_mask:0xf
	v_fmac_f32_dpp v71, v73, v129 row_shl:15 row_mask:0xf bank_mask:0xf
	v_fmac_f32_dpp v71, v63, v125 row_shr:2 row_mask:0xf bank_mask:0xf
	v_fmac_f32_dpp v71, v73, v125 row_shl:14 row_mask:0xf bank_mask:0xf
	v_pk_fma_f32 v[76:77], v[56:57], v[114:115], v[118:119]
	v_fmac_f32_dpp v76, v56, v106 row_shr:1 row_mask:0xf bank_mask:0xf
	v_fmac_f32_dpp v76, v66, v106 row_shl:15 row_mask:0xf bank_mask:0xf
	v_fmac_f32_dpp v76, v56, v102 row_shr:2 row_mask:0xf bank_mask:0xf
	v_fmac_f32_dpp v76, v66, v102 row_shl:14 row_mask:0xf bank_mask:0xf
	v_fmac_f32_dpp v77, v57, v107 row_shr:1 row_mask:0xf bank_mask:0xf
	v_fmac_f32_dpp v77, v67, v107 row_shl:15 row_mask:0xf bank_mask:0xf
	v_fmac_f32_dpp v77, v57, v103 row_shr:2 row_mask:0xf bank_mask:0xf
	v_fmac_f32_dpp v77, v67, v103 row_shl:14 row_mask:0xf bank_mask:0xf
	v_pk_fma_f32 v[66:67], v[58:59], v[116:117], v[120:121]
	v_fmac_f32_dpp v66, v58, v108 row_shr:1 row_mask:0xf bank_mask:0xf
	v_fmac_f32_dpp v66, v68, v108 row_shl:15 row_mask:0xf bank_mask:0xf
	v_fmac_f32_dpp v66, v58, v104 row_shr:2 row_mask:0xf bank_mask:0xf
	v_fmac_f32_dpp v66, v68, v104 row_shl:14 row_mask:0xf bank_mask:0xf
	v_fmac_f32_dpp v67, v59, v109 row_shr:1 row_mask:0xf bank_mask:0xf
	v_fmac_f32_dpp v67, v69, v109 row_shl:15 row_mask:0xf bank_mask:0xf
	v_fmac_f32_dpp v67, v59, v105 row_shr:2 row_mask:0xf bank_mask:0xf
	v_fmac_f32_dpp v67, v69, v105 row_shl:14 row_mask:0xf bank_mask:0xf
	s_mov_b64 s[34:35], -1
	s_and_b64 vcc, exec, s[46:47]
	v_add_u32_e32 v148, 0xfffff520, v111
	s_cbranch_vccnz .LBB0_283
	s_add_u32 s34, s55, s26
	s_addc_u32 s35, s58, s27
	s_mov_b64 s[34:35], 0

; DI unsigned pk2(float lo, float hi) { f32x2_t v = {lo, hi}; bf16x2_t b = __builtin_convertvector(v, bf16x2_t); return __builtin_bit_cast(unsigned, b); }
; template <int CTRL> DI float dppf(float v) { return __int_as_float(__builtin_amdgcn_mov_dpp(__float_as_int(v), CTRL, 0xf, 0xf, true)); }
;     DI void operator()(pg8::f32x4 (&acc)[2][2][4][2], const pg8::Unit& u, int wr, int wc, int fr, int fq) const {
;     ...
;                 for (int m = 0; m < 4; ++m) {
;                     float cv[2][4];
; #pragma unroll
;                     for (int bj = 0; bj < 2; ++bj) {
;                         const pg8::f32x4 cur = acc[ai][bj][m][n];
;                         pg8::f32x4 prv;
;                         if (m > 0) prv = acc[ai][bj][m > 0 ? m - 1 : 0][n]; else prv = (pg8::f32x4){hal[bj][0], hal[bj][1], hal[bj][2], hal[bj][3]};
; #pragma unroll
;                         for (int i = 0; i < 4; ++i) {
;                             const float q1 = dppf<0x121>(prv[i]), q2 = dppf<0x122>(prv[i]);
;                             const float p1 = __int_as_float(__builtin_amdgcn_update_dpp(__float_as_int(q1), __float_as_int(cur[i]), 0x111, 0xf, 0xf, false));
;                             const float p2 = __int_as_float(__builtin_amdgcn_update_dpp(__float_as_int(q2), __float_as_int(cur[i]), 0x112, 0xf, 0xf, false));
;                             cv[bj][i] = cb[bj][i] + w0[bj][i] * p2 + w1[bj][i] * p1 + w2[bj][i] * cur[i];
;                         }
;                     }
;                     float o[4];
; #pragma unroll
;                     for (int i = 0; i < 4; ++i) o[i] = gelu_tanh(cv[0][i]) * cv[1][i];
;                     const int row = u.pm * 256 + ai * 128 + wr * 64 + m * 16 + fr;
;                     v2u w; w.x = pk2(o[0], o[1]); w.y = pk2(o[2], o[3]);
;                     *(v2u*)(a_row(wsb, row) + u.pn * 128 + wc * 32 + 8 * fq + 4 * n) = w;
.LBB0_285:
	v_pk_mul_f32 v[98:99], v[84:85], v[84:85]
	v_pk_mul_f32 v[72:73], v[70:71], v[70:71]
	v_fmamk_f32 v98, v98, 0xbdd2d3e7, v175
	v_fmamk_f32 v99, v99, 0xbdd2d3e7, v175
	v_mul_f32_e32 v98, v84, v98
	v_mul_f32_e32 v99, v85, v99
	v_exp_f32_e32 v98, v98
	v_exp_f32_e32 v99, v99
	v_fmamk_f32 v72, v72, 0xbdd2d3e7, v175
	v_add_f32_e32 v98, 1.0, v98
	v_add_f32_e32 v99, 1.0, v99
	v_rcp_f32_e32 v98, v98
	v_rcp_f32_e32 v99, v99
	v_mul_f32_e32 v72, v70, v72
	v_pk_mul_f32 v[82:83], v[84:85], v[98:99]
	v_exp_f32_e32 v84, v72
	v_fmamk_f32 v72, v73, 0xbdd2d3e7, v175
	v_mul_f32_e32 v72, v71, v72
	v_exp_f32_e32 v85, v72
	v_pk_mul_f32 v[72:73], v[82:83], v[76:77]
	v_add_f32_e32 v76, 1.0, v84
	v_add_f32_e32 v77, 1.0, v85
	v_rcp_f32_e32 v76, v76
	v_rcp_f32_e32 v77, v77
	s_mov_b64 s[34:35], -1
	s_and_b64 vcc, exec, s[46:47]
	v_pk_mul_f32 v[68:69], v[70:71], v[76:77]
	v_pk_mul_f32 v[66:67], v[68:69], v[66:67]
	v_cvt_pk_bf16_f32 v248, v72, v73
	v_cvt_pk_bf16_f32 v249, v66, v67
	v_pk_fma_f32 v[72:73], v[94:95], v[130:131], v[134:135]
	v_fmac_f32_dpp v72, v94, v126 row_shr:1 row_mask:0xf bank_mask:0xf
	v_fmac_f32_dpp v72, v60, v126 row_shl:15 row_mask:0xf bank_mask:0xf
	v_fmac_f32_dpp v72, v94, v122 row_shr:2 row_mask:0xf bank_mask:0xf
	v_fmac_f32_dpp v72, v60, v122 row_shl:14 row_mask:0xf bank_mask:0xf
	v_fmac_f32_dpp v73, v95, v127 row_shr:1 row_mask:0xf bank_mask:0xf
	v_fmac_f32_dpp v73, v61, v127 row_shl:15 row_mask:0xf bank_mask:0xf
	v_fmac_f32_dpp v73, v95, v123 row_shr:2 row_mask:0xf bank_mask:0xf
	v_fmac_f32_dpp v73, v61, v123 row_shl:14 row_mask:0xf bank_mask:0xf
	v_pk_fma_f32 v[60:61], v[96:97], v[132:133], v[136:137]
	v_fmac_f32_dpp v60, v96, v128 row_shr:1 row_mask:0xf bank_mask:0xf
	v_fmac_f32_dpp v60, v62, v128 row_shl:15 row_mask:0xf bank_mask:0xf
	v_fmac_f32_dpp v60, v96, v124 row_shr:2 row_mask:0xf bank_mask:0xf
	v_fmac_f32_dpp v60, v62, v124 row_shl:14 row_mask:0xf bank_mask:0xf
	v_fmac_f32_dpp v61, v97, v129 row_shr:1 row_mask:0xf bank_mask:0xf
	v_fmac_f32_dpp v61, v63, v129 row_shl:15 row_mask:0xf bank_mask:0xf
	v_fmac_f32_dpp v61, v97, v125 row_shr:2 row_mask:0xf bank_mask:0xf
	v_fmac_f32_dpp v61, v63, v125 row_shl:14 row_mask:0xf bank_mask:0xf
	v_pk_fma_f32 v[68:69], v[90:91], v[114:115], v[118:119]
	v_fmac_f32_dpp v68, v90, v106 row_shr:1 row_mask:0xf bank_mask:0xf
	v_fmac_f32_dpp v68, v56, v106 row_shl:15 row_mask:0xf bank_mask:0xf
	v_fmac_f32_dpp v68, v90, v102 row_shr:2 row_mask:0xf bank_mask:0xf
	v_fmac_f32_dpp v68, v56, v102 row_shl:14 row_mask:0xf bank_mask:0xf
	v_fmac_f32_dpp v69, v91, v107 row_shr:1 row_mask:0xf bank_mask:0xf
	v_fmac_f32_dpp v69, v57, v107 row_shl:15 row_mask:0xf bank_mask:0xf
	v_fmac_f32_dpp v69, v91, v103 row_shr:2 row_mask:0xf bank_mask:0xf
	v_fmac_f32_dpp v69, v57, v103 row_shl:14 row_mask:0xf bank_mask:0xf
	v_pk_fma_f32 v[56:57], v[92:93], v[116:117], v[120:121]
	v_fmac_f32_dpp v56, v92, v108 row_shr:1 row_mask:0xf bank_mask:0xf
	v_fmac_f32_dpp v56, v58, v108 row_shl:15 row_mask:0xf bank_mask:0xf
	v_fmac_f32_dpp v56, v92, v104 row_shr:2 row_mask:0xf bank_mask:0xf
	v_fmac_f32_dpp v56, v58, v104 row_shl:14 row_mask:0xf bank_mask:0xf
	v_fmac_f32_dpp v57, v93, v109 row_shr:1 row_mask:0xf bank_mask:0xf
	v_fmac_f32_dpp v57, v59, v109 row_shl:15 row_mask:0xf bank_mask:0xf
	v_fmac_f32_dpp v57, v93, v105 row_shr:2 row_mask:0xf bank_mask:0xf
	v_fmac_f32_dpp v57, v59, v105 row_shl:14 row_mask:0xf bank_mask:0xf
	v_add_u32_e32 v149, 0xfffff530, v111
	s_cbranch_vccnz .LBB0_287
	s_add_u32 s34, s55, s26
	s_addc_u32 s35, s58, s27
	s_mov_b64 s[34:35], 0

; DI unsigned pk2(float lo, float hi) { f32x2_t v = {lo, hi}; bf16x2_t b = __builtin_convertvector(v, bf16x2_t); return __builtin_bit_cast(unsigned, b); }
;     DI void operator()(pg8::f32x4 (&acc)[2][2][4][2], const pg8::Unit& u, int wr, int wc, int fr, int fq) const {
;     ...
;         for (int n = 0; n < 2; ++n) {
;             v4f w0[2], w1[2], w2[2], cb[2];
; #pragma unroll
;             for (int bj = 0; bj < 2; ++bj) {
;                 const float* p = cwp + u.pn * 256 + bj * 128 + wc * 32 + 8 * fq + 4 * n;
;                 w0[bj] = *(const v4f*)p; w1[bj] = *(const v4f*)(p + NUP); w2[bj] = *(const v4f*)(p + 2 * NUP); cb[bj] = *(const v4f*)(p + 3 * NUP);
;             }
;     ...
;                     float o[4];
; #pragma unroll
;                     for (int i = 0; i < 4; ++i) o[i] = gelu_tanh(cv[0][i]) * cv[1][i];
;                     const int row = u.pm * 256 + ai * 128 + wr * 64 + m * 16 + fr;
;                     v2u w; w.x = pk2(o[0], o[1]); w.y = pk2(o[2], o[3]);
;                     *(v2u*)(a_row(wsb, row) + u.pn * 128 + wc * 32 + 8 * fq + 4 * n) = w;
.LBB0_289:
	v_pk_mul_f32 v[74:75], v[72:73], v[72:73]
	v_pk_mul_f32 v[62:63], v[60:61], v[60:61]
	v_fmamk_f32 v74, v74, 0xbdd2d3e7, v175
	v_fmamk_f32 v75, v75, 0xbdd2d3e7, v175
	v_mul_f32_e32 v74, v72, v74
	v_mul_f32_e32 v75, v73, v75
	v_exp_f32_e32 v74, v74
	v_exp_f32_e32 v75, v75
	v_fmamk_f32 v62, v62, 0xbdd2d3e7, v175
	v_add_f32_e32 v74, 1.0, v74
	v_add_f32_e32 v75, 1.0, v75
	v_rcp_f32_e32 v74, v74
	v_rcp_f32_e32 v75, v75
	v_mul_f32_e32 v62, v60, v62
	v_pk_mul_f32 v[70:71], v[72:73], v[74:75]
	v_exp_f32_e32 v72, v62
	v_fmamk_f32 v62, v63, 0xbdd2d3e7, v175
	v_mul_f32_e32 v62, v61, v62
	v_exp_f32_e32 v73, v62
	v_pk_mul_f32 v[62:63], v[70:71], v[68:69]
	v_add_f32_e32 v68, 1.0, v72
	v_add_f32_e32 v69, 1.0, v73
	v_rcp_f32_e32 v68, v68
	v_rcp_f32_e32 v69, v69
	v_mov_b32_e32 v98, 0
	v_mov_b32_e32 v102, 0
	v_pk_mul_f32 v[58:59], v[60:61], v[68:69]
	v_add_co_u32_e32 v60, vcc, 0x5000, v202
	v_pk_mul_f32 v[56:57], v[58:59], v[56:57]
	s_nop 0
	v_addc_co_u32_e32 v61, vcc, 0, v203, vcc
	v_cvt_pk_bf16_f32 v251, v56, v57
	v_add_co_u32_e32 v66, vcc, 0xb000, v202
	s_nop 0
	v_addc_co_u32_e32 v67, vcc, 0, v203, vcc
	v_cvt_pk_bf16_f32 v250, v62, v63
	v_add_co_u32_e32 v70, vcc, 0x10000, v202
	s_nop 0
	v_addc_co_u32_e32 v71, vcc, 0, v203, vcc
	global_load_dwordx4 v[74:77], v[202:203], off offset:16
	global_load_dwordx4 v[56:59], v[202:203], off offset:528
	global_load_dwordx4 v[82:85], v[60:61], off offset:2064
	s_nop 0
	global_load_dwordx4 v[60:63], v[60:61], off offset:2576
	s_nop 0
	global_load_dwordx4 v[90:93], v[66:67], off offset:16
	s_nop 0
	global_load_dwordx4 v[66:69], v[66:67], off offset:528
	s_nop 0
	global_load_dwordx4 v[94:97], v[70:71], off offset:2064
	s_nop 0
	global_load_dwordx4 v[70:73], v[70:71], off offset:2576
	s_and_b64 vcc, exec, s[42:43]
	v_mov_b32_e32 v103, 0
	v_mov_b32_e32 v104, 0
	v_mov_b32_e32 v105, 0
	s_cbranch_vccnz .LBB0_291
	ds_read_b128 v[102:105], v193 offset:128

; template <int CTRL> DI float dppf(float v) { return __int_as_float(__builtin_amdgcn_mov_dpp(__float_as_int(v), CTRL, 0xf, 0xf, true)); }
;     DI void operator()(pg8::f32x4 (&acc)[2][2][4][2], const pg8::Unit& u, int wr, int wc, int fr, int fq) const {
;     ...
;             for (int ai = 0; ai < 2; ++ai) {
;                 v4f hal[2];
;                 {
;                     const bool has = (wr == 1) || (ai == 1);
;                     const int as = (wr == 1) ? ai : 0, ws_ = (wr == 1) ? 0 : 1;
; #pragma unroll
;                     for (int bj = 0; bj < 2; ++bj) { v4f hv = H[(((as * 2 + ws_) * 4 + wc) * 4 + bj * 2 + n) * 8 + hl]; hal[bj] = has ? hv : (v4f){0.f, 0.f, 0.f, 0.f}; }
;                 }
; #pragma unroll
;                 for (int m = 0; m < 4; ++m) {
;                     float cv[2][4];
; #pragma unroll
;                     for (int bj = 0; bj < 2; ++bj) {
;                         const pg8::f32x4 cur = acc[ai][bj][m][n];
;                         pg8::f32x4 prv;
;                         if (m > 0) prv = acc[ai][bj][m > 0 ? m - 1 : 0][n]; else prv = (pg8::f32x4){hal[bj][0], hal[bj][1], hal[bj][2], hal[bj][3]};
; #pragma unroll
;                         for (int i = 0; i < 4; ++i) {
;                             const float q1 = dppf<0x121>(prv[i]), q2 = dppf<0x122>(prv[i]);
;                             const float p1 = __int_as_float(__builtin_amdgcn_update_dpp(__float_as_int(q1), __float_as_int(cur[i]), 0x111, 0xf, 0xf, false));
;                             const float p2 = __int_as_float(__builtin_amdgcn_update_dpp(__float_as_int(q2), __float_as_int(cur[i]), 0x112, 0xf, 0xf, false));
;                             cv[bj][i] = cb[bj][i] + w0[bj][i] * p2 + w1[bj][i] * p1 + w2[bj][i] * cur[i];
;                         }
;                     }
.LBB0_293:
	s_waitcnt lgkmcnt(0)
	s_waitcnt vmcnt(0)
	v_pk_fma_f32 v[116:117], v[86:87], v[90:91], v[94:95]
	v_fmac_f32_dpp v116, v86, v82 row_shr:1 row_mask:0xf bank_mask:0xf
	v_fmac_f32_dpp v116, v102, v82 row_shl:15 row_mask:0xf bank_mask:0xf
	v_fmac_f32_dpp v116, v86, v74 row_shr:2 row_mask:0xf bank_mask:0xf
	v_fmac_f32_dpp v116, v102, v74 row_shl:14 row_mask:0xf bank_mask:0xf
	v_fmac_f32_dpp v117, v87, v83 row_shr:1 row_mask:0xf bank_mask:0xf
	v_fmac_f32_dpp v117, v103, v83 row_shl:15 row_mask:0xf bank_mask:0xf
	v_fmac_f32_dpp v117, v87, v75 row_shr:2 row_mask:0xf bank_mask:0xf
	v_fmac_f32_dpp v117, v103, v75 row_shl:14 row_mask:0xf bank_mask:0xf
	v_pk_fma_f32 v[102:103], v[88:89], v[92:93], v[96:97]
	v_fmac_f32_dpp v102, v88, v84 row_shr:1 row_mask:0xf bank_mask:0xf
	v_fmac_f32_dpp v102, v104, v84 row_shl:15 row_mask:0xf bank_mask:0xf
	v_fmac_f32_dpp v102, v88, v76 row_shr:2 row_mask:0xf bank_mask:0xf
	v_fmac_f32_dpp v102, v104, v76 row_shl:14 row_mask:0xf bank_mask:0xf
	v_fmac_f32_dpp v103, v89, v85 row_shr:1 row_mask:0xf bank_mask:0xf
	v_fmac_f32_dpp v103, v105, v85 row_shl:15 row_mask:0xf bank_mask:0xf
	v_fmac_f32_dpp v103, v89, v77 row_shr:2 row_mask:0xf bank_mask:0xf
	v_fmac_f32_dpp v103, v105, v77 row_shl:14 row_mask:0xf bank_mask:0xf
	v_pk_fma_f32 v[108:109], v[78:79], v[66:67], v[70:71]
	v_fmac_f32_dpp v108, v78, v60 row_shr:1 row_mask:0xf bank_mask:0xf
	v_fmac_f32_dpp v108, v98, v60 row_shl:15 row_mask:0xf bank_mask:0xf
	v_fmac_f32_dpp v108, v78, v56 row_shr:2 row_mask:0xf bank_mask:0xf
	v_fmac_f32_dpp v108, v98, v56 row_shl:14 row_mask:0xf bank_mask:0xf
	v_fmac_f32_dpp v109, v79, v61 row_shr:1 row_mask:0xf bank_mask:0xf
	v_fmac_f32_dpp v109, v99, v61 row_shl:15 row_mask:0xf bank_mask:0xf
	v_fmac_f32_dpp v109, v79, v57 row_shr:2 row_mask:0xf bank_mask:0xf
	v_fmac_f32_dpp v109, v99, v57 row_shl:14 row_mask:0xf bank_mask:0xf
	v_pk_fma_f32 v[98:99], v[80:81], v[68:69], v[72:73]
	v_fmac_f32_dpp v98, v80, v62 row_shr:1 row_mask:0xf bank_mask:0xf
	v_fmac_f32_dpp v98, v100, v62 row_shl:15 row_mask:0xf bank_mask:0xf
	v_fmac_f32_dpp v98, v80, v58 row_shr:2 row_mask:0xf bank_mask:0xf
	v_fmac_f32_dpp v98, v100, v58 row_shl:14 row_mask:0xf bank_mask:0xf
	v_fmac_f32_dpp v99, v81, v63 row_shr:1 row_mask:0xf bank_mask:0xf
	v_fmac_f32_dpp v99, v101, v63 row_shl:15 row_mask:0xf bank_mask:0xf
	v_fmac_f32_dpp v99, v81, v59 row_shr:2 row_mask:0xf bank_mask:0xf
	v_fmac_f32_dpp v99, v101, v59 row_shl:14 row_mask:0xf bank_mask:0xf
	s_and_b64 vcc, exec, s[44:45]
	s_mov_b64 s[34:35], -1
	s_cbranch_vccnz .LBB0_295
	s_add_u32 s34, s55, s24
	s_addc_u32 s35, s58, s25
	v_mov_b64_e32 v[104:105], s[34:35]
	v_mad_u64_u32 v[104:105], s[34:35], v195, s0, v[104:105]
	s_mov_b64 s[34:35], 0

; DI unsigned pk2(float lo, float hi) { f32x2_t v = {lo, hi}; bf16x2_t b = __builtin_convertvector(v, bf16x2_t); return __builtin_bit_cast(unsigned, b); }
; template <int CTRL> DI float dppf(float v) { return __int_as_float(__builtin_amdgcn_mov_dpp(__float_as_int(v), CTRL, 0xf, 0xf, true)); }
;     DI void operator()(pg8::f32x4 (&acc)[2][2][4][2], const pg8::Unit& u, int wr, int wc, int fr, int fq) const {
;     ...
;                 for (int m = 0; m < 4; ++m) {
;                     float cv[2][4];
; #pragma unroll
;                     for (int bj = 0; bj < 2; ++bj) {
;                         const pg8::f32x4 cur = acc[ai][bj][m][n];
;                         pg8::f32x4 prv;
;                         if (m > 0) prv = acc[ai][bj][m > 0 ? m - 1 : 0][n]; else prv = (pg8::f32x4){hal[bj][0], hal[bj][1], hal[bj][2], hal[bj][3]};
; #pragma unroll
;                         for (int i = 0; i < 4; ++i) {
;                             const float q1 = dppf<0x121>(prv[i]), q2 = dppf<0x122>(prv[i]);
;                             const float p1 = __int_as_float(__builtin_amdgcn_update_dpp(__float_as_int(q1), __float_as_int(cur[i]), 0x111, 0xf, 0xf, false));
;                             const float p2 = __int_as_float(__builtin_amdgcn_update_dpp(__float_as_int(q2), __float_as_int(cur[i]), 0x112, 0xf, 0xf, false));
;                             cv[bj][i] = cb[bj][i] + w0[bj][i] * p2 + w1[bj][i] * p1 + w2[bj][i] * cur[i];
;                         }
;                     }
;                     float o[4];
; #pragma unroll
;                     for (int i = 0; i < 4; ++i) o[i] = gelu_tanh(cv[0][i]) * cv[1][i];
;                     const int row = u.pm * 256 + ai * 128 + wr * 64 + m * 16 + fr;
;                     v2u w; w.x = pk2(o[0], o[1]); w.y = pk2(o[2], o[3]);
;                     *(v2u*)(a_row(wsb, row) + u.pn * 128 + wc * 32 + 8 * fq + 4 * n) = w;
.LBB0_297:
	s_waitcnt vmcnt(1)
	v_pk_mul_f32 v[118:119], v[116:117], v[116:117]
	v_pk_mul_f32 v[106:107], v[102:103], v[102:103]
	v_fmamk_f32 v111, v118, 0xbdd2d3e7, v175
	v_mul_f32_e32 v111, v116, v111
	v_fmamk_f32 v113, v119, 0xbdd2d3e7, v175
	v_exp_f32_e32 v111, v111
	v_mul_f32_e32 v113, v117, v113
	v_exp_f32_e32 v113, v113
	v_fmamk_f32 v106, v106, 0xbdd2d3e7, v175
	v_add_f32_e32 v111, 1.0, v111
	v_rcp_f32_e32 v118, v111
	v_add_f32_e32 v111, 1.0, v113
	v_mul_f32_e32 v106, v102, v106
	v_rcp_f32_e32 v119, v111
	v_exp_f32_e32 v111, v106
	v_fmamk_f32 v106, v107, 0xbdd2d3e7, v175
	v_mul_f32_e32 v106, v103, v106
	v_exp_f32_e32 v113, v106
	s_waitcnt vmcnt(0)
	v_pk_mul_f32 v[114:115], v[116:117], v[118:119]
	v_pk_mul_f32 v[106:107], v[114:115], v[108:109]
	v_add_f32_e32 v108, 1.0, v111
	v_add_f32_e32 v109, 1.0, v113
	v_rcp_f32_e32 v108, v108
	v_rcp_f32_e32 v109, v109
	v_mov_b32_e32 v201, v200
	v_pk_mul_f32 v[44:45], v[44:45], v[200:201]
	v_pk_mul_f32 v[100:101], v[102:103], v[108:109]
	v_pk_mul_f32 v[40:41], v[40:41], v[200:201]
	v_pk_mul_f32 v[98:99], v[100:101], v[98:99]
	v_cvt_pk_bf16_f32 v246, v106, v107
	v_cvt_pk_bf16_f32 v247, v98, v99
	v_mov_b32_e32 v98, v200
	v_mov_b32_e32 v99, v200
	v_pk_mul_f32 v[46:47], v[46:47], v[98:99]
	v_pk_mul_f32 v[42:43], v[42:43], v[98:99]
	v_lshl_add_u64 v[98:99], s[22:23], 1, v[104:105]
	v_lshl_add_u64 v[98:99], v[98:99], 0, s[72:73]
	v_lshl_add_u64 v[98:99], v[98:99], 0, v[64:65]
	v_mov_b32_e32 v244, v220
	v_mov_b32_e32 v245, v221
	global_store_dwordx4 v[98:99], v[244:247], off
	v_pk_fma_f32 v[104:105], v[44:45], v[90:91], v[94:95]
	v_fmac_f32_dpp v104, v44, v82 row_shr:1 row_mask:0xf bank_mask:0xf
	v_fmac_f32_dpp v104, v86, v82 row_shl:15 row_mask:0xf bank_mask:0xf
	v_fmac_f32_dpp v104, v44, v74 row_shr:2 row_mask:0xf bank_mask:0xf
	v_fmac_f32_dpp v104, v86, v74 row_shl:14 row_mask:0xf bank_mask:0xf
	v_fmac_f32_dpp v105, v45, v83 row_shr:1 row_mask:0xf bank_mask:0xf
	v_fmac_f32_dpp v105, v87, v83 row_shl:15 row_mask:0xf bank_mask:0xf
	v_fmac_f32_dpp v105, v45, v75 row_shr:2 row_mask:0xf bank_mask:0xf
	v_fmac_f32_dpp v105, v87, v75 row_shl:14 row_mask:0xf bank_mask:0xf
	v_pk_fma_f32 v[86:87], v[46:47], v[92:93], v[96:97]
	v_fmac_f32_dpp v86, v46, v84 row_shr:1 row_mask:0xf bank_mask:0xf
	v_fmac_f32_dpp v86, v88, v84 row_shl:15 row_mask:0xf bank_mask:0xf
	v_fmac_f32_dpp v86, v46, v76 row_shr:2 row_mask:0xf bank_mask:0xf
	v_fmac_f32_dpp v86, v88, v76 row_shl:14 row_mask:0xf bank_mask:0xf
	v_fmac_f32_dpp v87, v47, v85 row_shr:1 row_mask:0xf bank_mask:0xf
	v_fmac_f32_dpp v87, v89, v85 row_shl:15 row_mask:0xf bank_mask:0xf
	v_fmac_f32_dpp v87, v47, v77 row_shr:2 row_mask:0xf bank_mask:0xf
	v_fmac_f32_dpp v87, v89, v77 row_shl:14 row_mask:0xf bank_mask:0xf
	v_pk_fma_f32 v[100:101], v[40:41], v[66:67], v[70:71]
	v_fmac_f32_dpp v100, v40, v60 row_shr:1 row_mask:0xf bank_mask:0xf
	v_fmac_f32_dpp v100, v78, v60 row_shl:15 row_mask:0xf bank_mask:0xf
	v_fmac_f32_dpp v100, v40, v56 row_shr:2 row_mask:0xf bank_mask:0xf
	v_fmac_f32_dpp v100, v78, v56 row_shl:14 row_mask:0xf bank_mask:0xf
	v_fmac_f32_dpp v101, v41, v61 row_shr:1 row_mask:0xf bank_mask:0xf
	v_fmac_f32_dpp v101, v79, v61 row_shl:15 row_mask:0xf bank_mask:0xf
	v_fmac_f32_dpp v101, v41, v57 row_shr:2 row_mask:0xf bank_mask:0xf
	v_fmac_f32_dpp v101, v79, v57 row_shl:14 row_mask:0xf bank_mask:0xf
	v_pk_fma_f32 v[78:79], v[42:43], v[68:69], v[72:73]
	v_fmac_f32_dpp v78, v42, v62 row_shr:1 row_mask:0xf bank_mask:0xf
	v_fmac_f32_dpp v78, v80, v62 row_shl:15 row_mask:0xf bank_mask:0xf
	v_fmac_f32_dpp v78, v42, v58 row_shr:2 row_mask:0xf bank_mask:0xf
	v_fmac_f32_dpp v78, v80, v58 row_shl:14 row_mask:0xf bank_mask:0xf
	v_fmac_f32_dpp v79, v43, v63 row_shr:1 row_mask:0xf bank_mask:0xf
	v_fmac_f32_dpp v79, v81, v63 row_shl:15 row_mask:0xf bank_mask:0xf
	v_fmac_f32_dpp v79, v43, v59 row_shr:2 row_mask:0xf bank_mask:0xf
	v_fmac_f32_dpp v79, v81, v59 row_shl:14 row_mask:0xf bank_mask:0xf
	s_and_b64 vcc, exec, s[44:45]
	s_mov_b64 s[34:35], -1
	s_cbranch_vccnz .LBB0_299
	s_add_u32 s34, s55, s24
	s_addc_u32 s35, s58, s25
	v_mov_b64_e32 v[98:99], s[34:35]
	v_mad_u64_u32 v[98:99], s[34:35], v199, s0, v[98:99]
	s_mov_b64 s[34:35], 0

; DI unsigned pk2(float lo, float hi) { f32x2_t v = {lo, hi}; bf16x2_t b = __builtin_convertvector(v, bf16x2_t); return __builtin_bit_cast(unsigned, b); }
; template <int CTRL> DI float dppf(float v) { return __int_as_float(__builtin_amdgcn_mov_dpp(__float_as_int(v), CTRL, 0xf, 0xf, true)); }
;     DI void operator()(pg8::f32x4 (&acc)[2][2][4][2], const pg8::Unit& u, int wr, int wc, int fr, int fq) const {
;     ...
;                 for (int m = 0; m < 4; ++m) {
;                     float cv[2][4];
; #pragma unroll
;                     for (int bj = 0; bj < 2; ++bj) {
;                         const pg8::f32x4 cur = acc[ai][bj][m][n];
;                         pg8::f32x4 prv;
;                         if (m > 0) prv = acc[ai][bj][m > 0 ? m - 1 : 0][n]; else prv = (pg8::f32x4){hal[bj][0], hal[bj][1], hal[bj][2], hal[bj][3]};
; #pragma unroll
;                         for (int i = 0; i < 4; ++i) {
;                             const float q1 = dppf<0x121>(prv[i]), q2 = dppf<0x122>(prv[i]);
;                             const float p1 = __int_as_float(__builtin_amdgcn_update_dpp(__float_as_int(q1), __float_as_int(cur[i]), 0x111, 0xf, 0xf, false));
;                             const float p2 = __int_as_float(__builtin_amdgcn_update_dpp(__float_as_int(q2), __float_as_int(cur[i]), 0x112, 0xf, 0xf, false));
;                             cv[bj][i] = cb[bj][i] + w0[bj][i] * p2 + w1[bj][i] * p1 + w2[bj][i] * cur[i];
;                         }
;                     }
;                     float o[4];
; #pragma unroll
;                     for (int i = 0; i < 4; ++i) o[i] = gelu_tanh(cv[0][i]) * cv[1][i];
;                     const int row = u.pm * 256 + ai * 128 + wr * 64 + m * 16 + fr;
;                     v2u w; w.x = pk2(o[0], o[1]); w.y = pk2(o[2], o[3]);
;                     *(v2u*)(a_row(wsb, row) + u.pn * 128 + wc * 32 + 8 * fq + 4 * n) = w;
.LBB0_301:
	v_pk_mul_f32 v[106:107], v[104:105], v[104:105]
	v_pk_mul_f32 v[88:89], v[86:87], v[86:87]
	v_fmamk_f32 v106, v106, 0xbdd2d3e7, v175
	v_fmamk_f32 v107, v107, 0xbdd2d3e7, v175
	v_mul_f32_e32 v106, v104, v106
	v_mul_f32_e32 v107, v105, v107
	v_exp_f32_e32 v106, v106
	v_exp_f32_e32 v107, v107
	v_fmamk_f32 v88, v88, 0xbdd2d3e7, v175
	v_add_f32_e32 v106, 1.0, v106
	v_add_f32_e32 v107, 1.0, v107
	v_rcp_f32_e32 v106, v106
	v_rcp_f32_e32 v107, v107
	v_mul_f32_e32 v88, v86, v88
	v_pk_mul_f32 v[102:103], v[104:105], v[106:107]
	v_exp_f32_e32 v104, v88
	v_fmamk_f32 v88, v89, 0xbdd2d3e7, v175
	v_mul_f32_e32 v88, v87, v88
	v_exp_f32_e32 v105, v88
	v_pk_mul_f32 v[88:89], v[102:103], v[100:101]
	v_add_f32_e32 v100, 1.0, v104
	v_add_f32_e32 v101, 1.0, v105
	v_rcp_f32_e32 v100, v100
	v_rcp_f32_e32 v101, v101
	v_mov_b32_e32 v199, v198
	v_pk_mul_f32 v[36:37], v[36:37], v[198:199]
	v_pk_mul_f32 v[80:81], v[86:87], v[100:101]
	v_pk_mul_f32 v[32:33], v[32:33], v[198:199]
	v_pk_mul_f32 v[78:79], v[80:81], v[78:79]
	v_cvt_pk_bf16_f32 v246, v88, v89
	v_cvt_pk_bf16_f32 v247, v78, v79
	v_mov_b32_e32 v78, v198
	v_mov_b32_e32 v79, v198
	v_pk_mul_f32 v[38:39], v[38:39], v[78:79]
	v_pk_mul_f32 v[34:35], v[34:35], v[78:79]
	v_lshl_add_u64 v[78:79], s[22:23], 1, v[98:99]
	v_lshl_add_u64 v[78:79], v[78:79], 0, s[72:73]
	v_lshl_add_u64 v[78:79], v[78:79], 0, v[64:65]
	v_mov_b32_e32 v244, v222
	v_mov_b32_e32 v245, v223
	global_store_dwordx4 v[78:79], v[244:247], off
	v_pk_fma_f32 v[88:89], v[36:37], v[90:91], v[94:95]
	v_fmac_f32_dpp v88, v36, v82 row_shr:1 row_mask:0xf bank_mask:0xf
	v_fmac_f32_dpp v88, v44, v82 row_shl:15 row_mask:0xf bank_mask:0xf
	v_fmac_f32_dpp v88, v36, v74 row_shr:2 row_mask:0xf bank_mask:0xf
	v_fmac_f32_dpp v88, v44, v74 row_shl:14 row_mask:0xf bank_mask:0xf
	v_fmac_f32_dpp v89, v37, v83 row_shr:1 row_mask:0xf bank_mask:0xf
	v_fmac_f32_dpp v89, v45, v83 row_shl:15 row_mask:0xf bank_mask:0xf
	v_fmac_f32_dpp v89, v37, v75 row_shr:2 row_mask:0xf bank_mask:0xf
	v_fmac_f32_dpp v89, v45, v75 row_shl:14 row_mask:0xf bank_mask:0xf
	v_pk_fma_f32 v[44:45], v[38:39], v[92:93], v[96:97]
	v_fmac_f32_dpp v44, v38, v84 row_shr:1 row_mask:0xf bank_mask:0xf
	v_fmac_f32_dpp v44, v46, v84 row_shl:15 row_mask:0xf bank_mask:0xf
	v_fmac_f32_dpp v44, v38, v76 row_shr:2 row_mask:0xf bank_mask:0xf
	v_fmac_f32_dpp v44, v46, v76 row_shl:14 row_mask:0xf bank_mask:0xf
	v_fmac_f32_dpp v45, v39, v85 row_shr:1 row_mask:0xf bank_mask:0xf
	v_fmac_f32_dpp v45, v47, v85 row_shl:15 row_mask:0xf bank_mask:0xf
	v_fmac_f32_dpp v45, v39, v77 row_shr:2 row_mask:0xf bank_mask:0xf
	v_fmac_f32_dpp v45, v47, v77 row_shl:14 row_mask:0xf bank_mask:0xf
	v_pk_fma_f32 v[80:81], v[32:33], v[66:67], v[70:71]
	v_fmac_f32_dpp v80, v32, v60 row_shr:1 row_mask:0xf bank_mask:0xf
	v_fmac_f32_dpp v80, v40, v60 row_shl:15 row_mask:0xf bank_mask:0xf
	v_fmac_f32_dpp v80, v32, v56 row_shr:2 row_mask:0xf bank_mask:0xf
	v_fmac_f32_dpp v80, v40, v56 row_shl:14 row_mask:0xf bank_mask:0xf
	v_fmac_f32_dpp v81, v33, v61 row_shr:1 row_mask:0xf bank_mask:0xf
	v_fmac_f32_dpp v81, v41, v61 row_shl:15 row_mask:0xf bank_mask:0xf
	v_fmac_f32_dpp v81, v33, v57 row_shr:2 row_mask:0xf bank_mask:0xf
	v_fmac_f32_dpp v81, v41, v57 row_shl:14 row_mask:0xf bank_mask:0xf
	v_pk_fma_f32 v[40:41], v[34:35], v[68:69], v[72:73]
	v_fmac_f32_dpp v40, v34, v62 row_shr:1 row_mask:0xf bank_mask:0xf
	v_fmac_f32_dpp v40, v42, v62 row_shl:15 row_mask:0xf bank_mask:0xf
	v_fmac_f32_dpp v40, v34, v58 row_shr:2 row_mask:0xf bank_mask:0xf
	v_fmac_f32_dpp v40, v42, v58 row_shl:14 row_mask:0xf bank_mask:0xf
	v_fmac_f32_dpp v41, v35, v63 row_shr:1 row_mask:0xf bank_mask:0xf
	v_fmac_f32_dpp v41, v43, v63 row_shl:15 row_mask:0xf bank_mask:0xf
	v_fmac_f32_dpp v41, v35, v59 row_shr:2 row_mask:0xf bank_mask:0xf
	v_fmac_f32_dpp v41, v43, v59 row_shl:14 row_mask:0xf bank_mask:0xf
	s_and_b64 vcc, exec, s[44:45]
	s_mov_b64 s[34:35], -1
	s_cbranch_vccnz .LBB0_303
	s_add_u32 s34, s55, s24
	s_addc_u32 s35, s58, s25
	v_mov_b64_e32 v[78:79], s[34:35]
	v_mad_u64_u32 v[78:79], s[34:35], v197, s0, v[78:79]
	s_mov_b64 s[34:35], 0

; DI unsigned pk2(float lo, float hi) { f32x2_t v = {lo, hi}; bf16x2_t b = __builtin_convertvector(v, bf16x2_t); return __builtin_bit_cast(unsigned, b); }
; template <int CTRL> DI float dppf(float v) { return __int_as_float(__builtin_amdgcn_mov_dpp(__float_as_int(v), CTRL, 0xf, 0xf, true)); }
;     DI void operator()(pg8::f32x4 (&acc)[2][2][4][2], const pg8::Unit& u, int wr, int wc, int fr, int fq) const {
;     ...
;                 for (int m = 0; m < 4; ++m) {
;                     float cv[2][4];
; #pragma unroll
;                     for (int bj = 0; bj < 2; ++bj) {
;                         const pg8::f32x4 cur = acc[ai][bj][m][n];
;                         pg8::f32x4 prv;
;                         if (m > 0) prv = acc[ai][bj][m > 0 ? m - 1 : 0][n]; else prv = (pg8::f32x4){hal[bj][0], hal[bj][1], hal[bj][2], hal[bj][3]};
; #pragma unroll
;                         for (int i = 0; i < 4; ++i) {
;                             const float q1 = dppf<0x121>(prv[i]), q2 = dppf<0x122>(prv[i]);
;                             const float p1 = __int_as_float(__builtin_amdgcn_update_dpp(__float_as_int(q1), __float_as_int(cur[i]), 0x111, 0xf, 0xf, false));
;                             const float p2 = __int_as_float(__builtin_amdgcn_update_dpp(__float_as_int(q2), __float_as_int(cur[i]), 0x112, 0xf, 0xf, false));
;                             cv[bj][i] = cb[bj][i] + w0[bj][i] * p2 + w1[bj][i] * p1 + w2[bj][i] * cur[i];
;                         }
;                     }
;                     float o[4];
; #pragma unroll
;                     for (int i = 0; i < 4; ++i) o[i] = gelu_tanh(cv[0][i]) * cv[1][i];
;                     const int row = u.pm * 256 + ai * 128 + wr * 64 + m * 16 + fr;
;                     v2u w; w.x = pk2(o[0], o[1]); w.y = pk2(o[2], o[3]);
;                     *(v2u*)(a_row(wsb, row) + u.pn * 128 + wc * 32 + 8 * fq + 4 * n) = w;
.LBB0_305:
	v_pk_mul_f32 v[98:99], v[88:89], v[88:89]
	v_pk_mul_f32 v[46:47], v[44:45], v[44:45]
	v_fmamk_f32 v98, v98, 0xbdd2d3e7, v175
	v_fmamk_f32 v99, v99, 0xbdd2d3e7, v175
	v_mul_f32_e32 v98, v88, v98
	v_mul_f32_e32 v99, v89, v99
	v_exp_f32_e32 v98, v98
	v_exp_f32_e32 v99, v99
	v_fmamk_f32 v46, v46, 0xbdd2d3e7, v175
	v_add_f32_e32 v98, 1.0, v98
	v_add_f32_e32 v99, 1.0, v99
	v_rcp_f32_e32 v98, v98
	v_rcp_f32_e32 v99, v99
	v_mul_f32_e32 v46, v44, v46
	v_pk_mul_f32 v[86:87], v[88:89], v[98:99]
	v_exp_f32_e32 v88, v46
	v_fmamk_f32 v46, v47, 0xbdd2d3e7, v175
	v_mul_f32_e32 v46, v45, v46
	v_exp_f32_e32 v89, v46
	v_pk_mul_f32 v[46:47], v[86:87], v[80:81]
	v_add_f32_e32 v80, 1.0, v88
	v_add_f32_e32 v81, 1.0, v89
	v_rcp_f32_e32 v80, v80
	v_rcp_f32_e32 v81, v81
	s_and_b64 vcc, exec, s[44:45]
	s_mov_b64 s[34:35], -1
	v_pk_mul_f32 v[42:43], v[44:45], v[80:81]
	v_pk_mul_f32 v[40:41], v[42:43], v[40:41]
	v_cvt_pk_bf16_f32 v246, v46, v47
	v_cvt_pk_bf16_f32 v247, v40, v41
	v_lshl_add_u64 v[40:41], s[22:23], 1, v[78:79]
	v_lshl_add_u64 v[40:41], v[40:41], 0, s[72:73]
	v_lshl_add_u64 v[40:41], v[40:41], 0, v[64:65]
	v_mov_b32_e32 v244, v224
	v_mov_b32_e32 v245, v225
	global_store_dwordx4 v[40:41], v[244:247], off
	v_pk_fma_f32 v[46:47], v[52:53], v[90:91], v[94:95]
	v_fmac_f32_dpp v46, v52, v82 row_shr:1 row_mask:0xf bank_mask:0xf
	v_fmac_f32_dpp v46, v36, v82 row_shl:15 row_mask:0xf bank_mask:0xf
	v_fmac_f32_dpp v46, v52, v74 row_shr:2 row_mask:0xf bank_mask:0xf
	v_fmac_f32_dpp v46, v36, v74 row_shl:14 row_mask:0xf bank_mask:0xf
	v_fmac_f32_dpp v47, v53, v83 row_shr:1 row_mask:0xf bank_mask:0xf
	v_fmac_f32_dpp v47, v37, v83 row_shl:15 row_mask:0xf bank_mask:0xf
	v_fmac_f32_dpp v47, v53, v75 row_shr:2 row_mask:0xf bank_mask:0xf
	v_fmac_f32_dpp v47, v37, v75 row_shl:14 row_mask:0xf bank_mask:0xf
	v_pk_fma_f32 v[36:37], v[54:55], v[92:93], v[96:97]
	v_fmac_f32_dpp v36, v54, v84 row_shr:1 row_mask:0xf bank_mask:0xf
	v_fmac_f32_dpp v36, v38, v84 row_shl:15 row_mask:0xf bank_mask:0xf
	v_fmac_f32_dpp v36, v54, v76 row_shr:2 row_mask:0xf bank_mask:0xf
	v_fmac_f32_dpp v36, v38, v76 row_shl:14 row_mask:0xf bank_mask:0xf
	v_fmac_f32_dpp v37, v55, v85 row_shr:1 row_mask:0xf bank_mask:0xf
	v_fmac_f32_dpp v37, v39, v85 row_shl:15 row_mask:0xf bank_mask:0xf
	v_fmac_f32_dpp v37, v55, v77 row_shr:2 row_mask:0xf bank_mask:0xf
	v_fmac_f32_dpp v37, v39, v77 row_shl:14 row_mask:0xf bank_mask:0xf
	v_pk_fma_f32 v[42:43], v[48:49], v[66:67], v[70:71]
	v_fmac_f32_dpp v42, v48, v60 row_shr:1 row_mask:0xf bank_mask:0xf
	v_fmac_f32_dpp v42, v32, v60 row_shl:15 row_mask:0xf bank_mask:0xf
	v_fmac_f32_dpp v42, v48, v56 row_shr:2 row_mask:0xf bank_mask:0xf
	v_fmac_f32_dpp v42, v32, v56 row_shl:14 row_mask:0xf bank_mask:0xf
	v_fmac_f32_dpp v43, v49, v61 row_shr:1 row_mask:0xf bank_mask:0xf
	v_fmac_f32_dpp v43, v33, v61 row_shl:15 row_mask:0xf bank_mask:0xf
	v_fmac_f32_dpp v43, v49, v57 row_shr:2 row_mask:0xf bank_mask:0xf
	v_fmac_f32_dpp v43, v33, v57 row_shl:14 row_mask:0xf bank_mask:0xf
	v_pk_fma_f32 v[32:33], v[50:51], v[68:69], v[72:73]
	v_fmac_f32_dpp v32, v50, v62 row_shr:1 row_mask:0xf bank_mask:0xf
	v_fmac_f32_dpp v32, v34, v62 row_shl:15 row_mask:0xf bank_mask:0xf
	v_fmac_f32_dpp v32, v50, v58 row_shr:2 row_mask:0xf bank_mask:0xf
	v_fmac_f32_dpp v32, v34, v58 row_shl:14 row_mask:0xf bank_mask:0xf
	v_fmac_f32_dpp v33, v51, v63 row_shr:1 row_mask:0xf bank_mask:0xf
	v_fmac_f32_dpp v33, v35, v63 row_shl:15 row_mask:0xf bank_mask:0xf
	v_fmac_f32_dpp v33, v51, v59 row_shr:2 row_mask:0xf bank_mask:0xf
	v_fmac_f32_dpp v33, v35, v59 row_shl:14 row_mask:0xf bank_mask:0xf
	s_cbranch_vccnz .LBB0_307
	s_add_u32 s24, s55, s24
	s_addc_u32 s25, s58, s25
	v_mov_b64_e32 v[40:41], s[24:25]
	v_mad_u64_u32 v[40:41], s[24:25], v164, s0, v[40:41]
	s_mov_b64 s[34:35], 0

; DI unsigned pk2(float lo, float hi) { f32x2_t v = {lo, hi}; bf16x2_t b = __builtin_convertvector(v, bf16x2_t); return __builtin_bit_cast(unsigned, b); }
; template <int CTRL> DI float dppf(float v) { return __int_as_float(__builtin_amdgcn_mov_dpp(__float_as_int(v), CTRL, 0xf, 0xf, true)); }
;     DI void operator()(pg8::f32x4 (&acc)[2][2][4][2], const pg8::Unit& u, int wr, int wc, int fr, int fq) const {
;     ...
;             for (int ai = 0; ai < 2; ++ai) {
;                 v4f hal[2];
;                 {
;                     const bool has = (wr == 1) || (ai == 1);
;                     const int as = (wr == 1) ? ai : 0, ws_ = (wr == 1) ? 0 : 1;
; #pragma unroll
;                     for (int bj = 0; bj < 2; ++bj) { v4f hv = H[(((as * 2 + ws_) * 4 + wc) * 4 + bj * 2 + n) * 8 + hl]; hal[bj] = has ? hv : (v4f){0.f, 0.f, 0.f, 0.f}; }
;                 }
; #pragma unroll
;                 for (int m = 0; m < 4; ++m) {
;                     float cv[2][4];
; #pragma unroll
;                     for (int bj = 0; bj < 2; ++bj) {
;                         const pg8::f32x4 cur = acc[ai][bj][m][n];
;                         pg8::f32x4 prv;
;                         if (m > 0) prv = acc[ai][bj][m > 0 ? m - 1 : 0][n]; else prv = (pg8::f32x4){hal[bj][0], hal[bj][1], hal[bj][2], hal[bj][3]};
; #pragma unroll
;                         for (int i = 0; i < 4; ++i) {
;                             const float q1 = dppf<0x121>(prv[i]), q2 = dppf<0x122>(prv[i]);
;                             const float p1 = __int_as_float(__builtin_amdgcn_update_dpp(__float_as_int(q1), __float_as_int(cur[i]), 0x111, 0xf, 0xf, false));
;                             const float p2 = __int_as_float(__builtin_amdgcn_update_dpp(__float_as_int(q2), __float_as_int(cur[i]), 0x112, 0xf, 0xf, false));
;                             cv[bj][i] = cb[bj][i] + w0[bj][i] * p2 + w1[bj][i] * p1 + w2[bj][i] * cur[i];
;                         }
;                     }
;                     float o[4];
; #pragma unroll
;                     for (int i = 0; i < 4; ++i) o[i] = gelu_tanh(cv[0][i]) * cv[1][i];
;                     const int row = u.pm * 256 + ai * 128 + wr * 64 + m * 16 + fr;
;                     v2u w; w.x = pk2(o[0], o[1]); w.y = pk2(o[2], o[3]);
;                     *(v2u*)(a_row(wsb, row) + u.pn * 128 + wc * 32 + 8 * fq + 4 * n) = w;
.LBB0_309:
	v_pk_mul_f32 v[52:53], v[46:47], v[46:47]
	v_pk_mul_f32 v[38:39], v[36:37], v[36:37]
	v_fmamk_f32 v52, v52, 0xbdd2d3e7, v175
	v_fmamk_f32 v53, v53, 0xbdd2d3e7, v175
	v_mul_f32_e32 v52, v46, v52
	v_mul_f32_e32 v53, v47, v53
	v_exp_f32_e32 v52, v52
	v_exp_f32_e32 v53, v53
	v_fmamk_f32 v38, v38, 0xbdd2d3e7, v175
	v_add_f32_e32 v52, 1.0, v52
	v_add_f32_e32 v53, 1.0, v53
	v_rcp_f32_e32 v52, v52
	v_rcp_f32_e32 v53, v53
	v_mul_f32_e32 v38, v36, v38
	v_pk_mul_f32 v[44:45], v[46:47], v[52:53]
	v_exp_f32_e32 v46, v38
	v_fmamk_f32 v38, v39, 0xbdd2d3e7, v175
	v_mul_f32_e32 v38, v37, v38
	v_exp_f32_e32 v47, v38
	v_pk_mul_f32 v[38:39], v[44:45], v[42:43]
	v_add_f32_e32 v42, 1.0, v46
	v_add_f32_e32 v43, 1.0, v47
	v_rcp_f32_e32 v42, v42
	v_rcp_f32_e32 v43, v43
	ds_read_b128 v[50:53], v218 offset:384
	v_cvt_pk_bf16_f32 v246, v38, v39
	v_pk_mul_f32 v[34:35], v[36:37], v[42:43]
	v_mov_b32_e32 v197, v196
	v_pk_mul_f32 v[32:33], v[34:35], v[32:33]
	ds_read_b128 v[34:37], v218 offset:128
	v_cvt_pk_bf16_f32 v247, v32, v33
	v_mov_b32_e32 v32, v196
	v_mov_b32_e32 v33, v196
	v_pk_mul_f32 v[22:23], v[22:23], v[32:33]
	v_pk_mul_f32 v[18:19], v[18:19], v[32:33]
	v_lshl_add_u64 v[32:33], s[22:23], 1, v[40:41]
	v_lshl_add_u64 v[32:33], v[32:33], 0, s[72:73]
	v_lshl_add_u64 v[32:33], v[32:33], 0, v[64:65]
	v_pk_mul_f32 v[20:21], v[20:21], v[196:197]
	v_pk_mul_f32 v[16:17], v[16:17], v[196:197]
	v_mov_b32_e32 v244, v232
	v_mov_b32_e32 v245, v233
	global_store_dwordx4 v[32:33], v[244:247], off
	s_waitcnt lgkmcnt(0)
	v_pk_fma_f32 v[46:47], v[20:21], v[90:91], v[94:95]
	v_fmac_f32_dpp v46, v20, v82 row_shr:1 row_mask:0xf bank_mask:0xf
	v_fmac_f32_dpp v46, v34, v82 row_shl:15 row_mask:0xf bank_mask:0xf
	v_fmac_f32_dpp v46, v20, v74 row_shr:2 row_mask:0xf bank_mask:0xf
	v_fmac_f32_dpp v46, v34, v74 row_shl:14 row_mask:0xf bank_mask:0xf
	v_fmac_f32_dpp v47, v21, v83 row_shr:1 row_mask:0xf bank_mask:0xf
	v_fmac_f32_dpp v47, v35, v83 row_shl:15 row_mask:0xf bank_mask:0xf
	v_fmac_f32_dpp v47, v21, v75 row_shr:2 row_mask:0xf bank_mask:0xf
	v_fmac_f32_dpp v47, v35, v75 row_shl:14 row_mask:0xf bank_mask:0xf
	v_pk_fma_f32 v[34:35], v[22:23], v[92:93], v[96:97]
	v_fmac_f32_dpp v34, v22, v84 row_shr:1 row_mask:0xf bank_mask:0xf
	v_fmac_f32_dpp v34, v36, v84 row_shl:15 row_mask:0xf bank_mask:0xf
	v_fmac_f32_dpp v34, v22, v76 row_shr:2 row_mask:0xf bank_mask:0xf
	v_fmac_f32_dpp v34, v36, v76 row_shl:14 row_mask:0xf bank_mask:0xf
	v_fmac_f32_dpp v35, v23, v85 row_shr:1 row_mask:0xf bank_mask:0xf
	v_fmac_f32_dpp v35, v37, v85 row_shl:15 row_mask:0xf bank_mask:0xf
	v_fmac_f32_dpp v35, v23, v77 row_shr:2 row_mask:0xf bank_mask:0xf
	v_fmac_f32_dpp v35, v37, v77 row_shl:14 row_mask:0xf bank_mask:0xf
	v_pk_fma_f32 v[42:43], v[16:17], v[66:67], v[70:71]
	v_fmac_f32_dpp v42, v16, v60 row_shr:1 row_mask:0xf bank_mask:0xf
	v_fmac_f32_dpp v42, v50, v60 row_shl:15 row_mask:0xf bank_mask:0xf
	v_fmac_f32_dpp v42, v16, v56 row_shr:2 row_mask:0xf bank_mask:0xf
	v_fmac_f32_dpp v42, v50, v56 row_shl:14 row_mask:0xf bank_mask:0xf
	v_fmac_f32_dpp v43, v17, v61 row_shr:1 row_mask:0xf bank_mask:0xf
	v_fmac_f32_dpp v43, v51, v61 row_shl:15 row_mask:0xf bank_mask:0xf
	v_fmac_f32_dpp v43, v17, v57 row_shr:2 row_mask:0xf bank_mask:0xf
	v_fmac_f32_dpp v43, v51, v57 row_shl:14 row_mask:0xf bank_mask:0xf
	v_pk_fma_f32 v[32:33], v[18:19], v[68:69], v[72:73]
	v_fmac_f32_dpp v32, v18, v62 row_shr:1 row_mask:0xf bank_mask:0xf
	v_fmac_f32_dpp v32, v52, v62 row_shl:15 row_mask:0xf bank_mask:0xf
	v_fmac_f32_dpp v32, v18, v58 row_shr:2 row_mask:0xf bank_mask:0xf
	v_fmac_f32_dpp v32, v52, v58 row_shl:14 row_mask:0xf bank_mask:0xf
	v_fmac_f32_dpp v33, v19, v63 row_shr:1 row_mask:0xf bank_mask:0xf
	v_fmac_f32_dpp v33, v53, v63 row_shl:15 row_mask:0xf bank_mask:0xf
	v_fmac_f32_dpp v33, v19, v59 row_shr:2 row_mask:0xf bank_mask:0xf
	v_fmac_f32_dpp v33, v53, v59 row_shl:14 row_mask:0xf bank_mask:0xf
	s_and_b64 vcc, exec, s[46:47]
	s_mov_b64 s[24:25], -1
	s_cbranch_vccnz .LBB0_311
	s_add_u32 s24, s55, s26
	s_addc_u32 s25, s58, s27
	v_mov_b64_e32 v[40:41], s[24:25]
	v_mad_u64_u32 v[40:41], s[24:25], v156, s0, v[40:41]
	s_mov_b64 s[24:25], 0

; DI unsigned pk2(float lo, float hi) { f32x2_t v = {lo, hi}; bf16x2_t b = __builtin_convertvector(v, bf16x2_t); return __builtin_bit_cast(unsigned, b); }
; template <int CTRL> DI float dppf(float v) { return __int_as_float(__builtin_amdgcn_mov_dpp(__float_as_int(v), CTRL, 0xf, 0xf, true)); }
;     DI void operator()(pg8::f32x4 (&acc)[2][2][4][2], const pg8::Unit& u, int wr, int wc, int fr, int fq) const {
;     ...
;                 for (int m = 0; m < 4; ++m) {
;                     float cv[2][4];
; #pragma unroll
;                     for (int bj = 0; bj < 2; ++bj) {
;                         const pg8::f32x4 cur = acc[ai][bj][m][n];
;                         pg8::f32x4 prv;
;                         if (m > 0) prv = acc[ai][bj][m > 0 ? m - 1 : 0][n]; else prv = (pg8::f32x4){hal[bj][0], hal[bj][1], hal[bj][2], hal[bj][3]};
; #pragma unroll
;                         for (int i = 0; i < 4; ++i) {
;                             const float q1 = dppf<0x121>(prv[i]), q2 = dppf<0x122>(prv[i]);
;                             const float p1 = __int_as_float(__builtin_amdgcn_update_dpp(__float_as_int(q1), __float_as_int(cur[i]), 0x111, 0xf, 0xf, false));
;                             const float p2 = __int_as_float(__builtin_amdgcn_update_dpp(__float_as_int(q2), __float_as_int(cur[i]), 0x112, 0xf, 0xf, false));
;                             cv[bj][i] = cb[bj][i] + w0[bj][i] * p2 + w1[bj][i] * p1 + w2[bj][i] * cur[i];
;                         }
;                     }
;                     float o[4];
; #pragma unroll
;                     for (int i = 0; i < 4; ++i) o[i] = gelu_tanh(cv[0][i]) * cv[1][i];
;                     const int row = u.pm * 256 + ai * 128 + wr * 64 + m * 16 + fr;
;                     v2u w; w.x = pk2(o[0], o[1]); w.y = pk2(o[2], o[3]);
;                     *(v2u*)(a_row(wsb, row) + u.pn * 128 + wc * 32 + 8 * fq + 4 * n) = w;
.LBB0_313:
	v_pk_mul_f32 v[48:49], v[46:47], v[46:47]
	v_pk_mul_f32 v[38:39], v[34:35], v[34:35]
	v_fmamk_f32 v48, v48, 0xbdd2d3e7, v175
	v_fmamk_f32 v49, v49, 0xbdd2d3e7, v175
	v_mul_f32_e32 v48, v46, v48
	v_mul_f32_e32 v49, v47, v49
	v_exp_f32_e32 v48, v48
	v_exp_f32_e32 v49, v49
	v_fmamk_f32 v38, v38, 0xbdd2d3e7, v175
	v_add_f32_e32 v48, 1.0, v48
	v_add_f32_e32 v49, 1.0, v49
	v_rcp_f32_e32 v48, v48
	v_rcp_f32_e32 v49, v49
	v_mul_f32_e32 v38, v34, v38
	v_pk_mul_f32 v[44:45], v[46:47], v[48:49]
	v_exp_f32_e32 v46, v38
	v_fmamk_f32 v38, v39, 0xbdd2d3e7, v175
	v_mul_f32_e32 v38, v35, v38
	v_exp_f32_e32 v47, v38
	v_pk_mul_f32 v[38:39], v[44:45], v[42:43]
	v_add_f32_e32 v42, 1.0, v46
	v_add_f32_e32 v43, 1.0, v47
	v_rcp_f32_e32 v42, v42
	v_rcp_f32_e32 v43, v43
	v_mov_b32_e32 v195, v194
	v_pk_mul_f32 v[12:13], v[12:13], v[194:195]
	v_pk_mul_f32 v[34:35], v[34:35], v[42:43]
	v_pk_mul_f32 v[8:9], v[8:9], v[194:195]
	v_pk_mul_f32 v[32:33], v[34:35], v[32:33]
	v_cvt_pk_bf16_f32 v246, v38, v39
	v_cvt_pk_bf16_f32 v247, v32, v33
	v_mov_b32_e32 v32, v194
	v_mov_b32_e32 v33, v194
	v_pk_mul_f32 v[14:15], v[14:15], v[32:33]
	v_pk_mul_f32 v[10:11], v[10:11], v[32:33]
	v_lshl_add_u64 v[32:33], s[22:23], 1, v[40:41]
	v_lshl_add_u64 v[32:33], v[32:33], 0, s[72:73]
	v_lshl_add_u64 v[32:33], v[32:33], 0, v[64:65]
	v_mov_b32_e32 v244, v238
	v_mov_b32_e32 v245, v239
	global_store_dwordx4 v[32:33], v[244:247], off
	v_pk_fma_f32 v[38:39], v[12:13], v[90:91], v[94:95]
	v_fmac_f32_dpp v38, v12, v82 row_shr:1 row_mask:0xf bank_mask:0xf
	v_fmac_f32_dpp v38, v20, v82 row_shl:15 row_mask:0xf bank_mask:0xf
	v_fmac_f32_dpp v38, v12, v74 row_shr:2 row_mask:0xf bank_mask:0xf
	v_fmac_f32_dpp v38, v20, v74 row_shl:14 row_mask:0xf bank_mask:0xf
	v_fmac_f32_dpp v39, v13, v83 row_shr:1 row_mask:0xf bank_mask:0xf
	v_fmac_f32_dpp v39, v21, v83 row_shl:15 row_mask:0xf bank_mask:0xf
	v_fmac_f32_dpp v39, v13, v75 row_shr:2 row_mask:0xf bank_mask:0xf
	v_fmac_f32_dpp v39, v21, v75 row_shl:14 row_mask:0xf bank_mask:0xf
	v_pk_fma_f32 v[20:21], v[14:15], v[92:93], v[96:97]
	v_fmac_f32_dpp v20, v14, v84 row_shr:1 row_mask:0xf bank_mask:0xf
	v_fmac_f32_dpp v20, v22, v84 row_shl:15 row_mask:0xf bank_mask:0xf
	v_fmac_f32_dpp v20, v14, v76 row_shr:2 row_mask:0xf bank_mask:0xf
	v_fmac_f32_dpp v20, v22, v76 row_shl:14 row_mask:0xf bank_mask:0xf
	v_fmac_f32_dpp v21, v15, v85 row_shr:1 row_mask:0xf bank_mask:0xf
	v_fmac_f32_dpp v21, v23, v85 row_shl:15 row_mask:0xf bank_mask:0xf
	v_fmac_f32_dpp v21, v15, v77 row_shr:2 row_mask:0xf bank_mask:0xf
	v_fmac_f32_dpp v21, v23, v77 row_shl:14 row_mask:0xf bank_mask:0xf
	v_pk_fma_f32 v[34:35], v[8:9], v[66:67], v[70:71]
	v_fmac_f32_dpp v34, v8, v60 row_shr:1 row_mask:0xf bank_mask:0xf
	v_fmac_f32_dpp v34, v16, v60 row_shl:15 row_mask:0xf bank_mask:0xf
	v_fmac_f32_dpp v34, v8, v56 row_shr:2 row_mask:0xf bank_mask:0xf
	v_fmac_f32_dpp v34, v16, v56 row_shl:14 row_mask:0xf bank_mask:0xf
	v_fmac_f32_dpp v35, v9, v61 row_shr:1 row_mask:0xf bank_mask:0xf
	v_fmac_f32_dpp v35, v17, v61 row_shl:15 row_mask:0xf bank_mask:0xf
	v_fmac_f32_dpp v35, v9, v57 row_shr:2 row_mask:0xf bank_mask:0xf
	v_fmac_f32_dpp v35, v17, v57 row_shl:14 row_mask:0xf bank_mask:0xf
	v_pk_fma_f32 v[16:17], v[10:11], v[68:69], v[72:73]
	v_fmac_f32_dpp v16, v10, v62 row_shr:1 row_mask:0xf bank_mask:0xf
	v_fmac_f32_dpp v16, v18, v62 row_shl:15 row_mask:0xf bank_mask:0xf
	v_fmac_f32_dpp v16, v10, v58 row_shr:2 row_mask:0xf bank_mask:0xf
	v_fmac_f32_dpp v16, v18, v58 row_shl:14 row_mask:0xf bank_mask:0xf
	v_fmac_f32_dpp v17, v11, v63 row_shr:1 row_mask:0xf bank_mask:0xf
	v_fmac_f32_dpp v17, v19, v63 row_shl:15 row_mask:0xf bank_mask:0xf
	v_fmac_f32_dpp v17, v11, v59 row_shr:2 row_mask:0xf bank_mask:0xf
	v_fmac_f32_dpp v17, v19, v59 row_shl:14 row_mask:0xf bank_mask:0xf
	s_and_b64 vcc, exec, s[46:47]
	s_mov_b64 s[24:25], -1
	s_cbranch_vccnz .LBB0_315
	s_add_u32 s24, s55, s26
	s_addc_u32 s25, s58, s27
	v_mov_b64_e32 v[32:33], s[24:25]
	v_mad_u64_u32 v[32:33], s[24:25], v150, s0, v[32:33]
	s_mov_b64 s[24:25], 0

; DI unsigned pk2(float lo, float hi) { f32x2_t v = {lo, hi}; bf16x2_t b = __builtin_convertvector(v, bf16x2_t); return __builtin_bit_cast(unsigned, b); }
; template <int CTRL> DI float dppf(float v) { return __int_as_float(__builtin_amdgcn_mov_dpp(__float_as_int(v), CTRL, 0xf, 0xf, true)); }
;     DI void operator()(pg8::f32x4 (&acc)[2][2][4][2], const pg8::Unit& u, int wr, int wc, int fr, int fq) const {
;     ...
;                 for (int m = 0; m < 4; ++m) {
;                     float cv[2][4];
; #pragma unroll
;                     for (int bj = 0; bj < 2; ++bj) {
;                         const pg8::f32x4 cur = acc[ai][bj][m][n];
;                         pg8::f32x4 prv;
;                         if (m > 0) prv = acc[ai][bj][m > 0 ? m - 1 : 0][n]; else prv = (pg8::f32x4){hal[bj][0], hal[bj][1], hal[bj][2], hal[bj][3]};
; #pragma unroll
;                         for (int i = 0; i < 4; ++i) {
;                             const float q1 = dppf<0x121>(prv[i]), q2 = dppf<0x122>(prv[i]);
;                             const float p1 = __int_as_float(__builtin_amdgcn_update_dpp(__float_as_int(q1), __float_as_int(cur[i]), 0x111, 0xf, 0xf, false));
;                             const float p2 = __int_as_float(__builtin_amdgcn_update_dpp(__float_as_int(q2), __float_as_int(cur[i]), 0x112, 0xf, 0xf, false));
;                             cv[bj][i] = cb[bj][i] + w0[bj][i] * p2 + w1[bj][i] * p1 + w2[bj][i] * cur[i];
;                         }
;                     }
;                     float o[4];
; #pragma unroll
;                     for (int i = 0; i < 4; ++i) o[i] = gelu_tanh(cv[0][i]) * cv[1][i];
;                     const int row = u.pm * 256 + ai * 128 + wr * 64 + m * 16 + fr;
;                     v2u w; w.x = pk2(o[0], o[1]); w.y = pk2(o[2], o[3]);
;                     *(v2u*)(a_row(wsb, row) + u.pn * 128 + wc * 32 + 8 * fq + 4 * n) = w;
.LBB0_317:
	v_pk_mul_f32 v[40:41], v[38:39], v[38:39]
	v_pk_mul_f32 v[22:23], v[20:21], v[20:21]
	v_fmamk_f32 v40, v40, 0xbdd2d3e7, v175
	v_fmamk_f32 v41, v41, 0xbdd2d3e7, v175
	v_mul_f32_e32 v40, v38, v40
	v_mul_f32_e32 v41, v39, v41
	v_exp_f32_e32 v40, v40
	v_exp_f32_e32 v41, v41
	v_fmamk_f32 v22, v22, 0xbdd2d3e7, v175
	v_add_f32_e32 v40, 1.0, v40
	v_add_f32_e32 v41, 1.0, v41
	v_rcp_f32_e32 v40, v40
	v_rcp_f32_e32 v41, v41
	v_mul_f32_e32 v22, v20, v22
	v_pk_mul_f32 v[36:37], v[38:39], v[40:41]
	v_exp_f32_e32 v38, v22
	v_fmamk_f32 v22, v23, 0xbdd2d3e7, v175
	v_mul_f32_e32 v22, v21, v22
	v_exp_f32_e32 v39, v22
	v_pk_mul_f32 v[22:23], v[36:37], v[34:35]
	v_add_f32_e32 v34, 1.0, v38
	v_add_f32_e32 v35, 1.0, v39
	v_rcp_f32_e32 v34, v34
	v_rcp_f32_e32 v35, v35
	v_mov_b32_e32 v193, v192
	v_pk_mul_f32 v[4:5], v[4:5], v[192:193]
	v_pk_mul_f32 v[18:19], v[20:21], v[34:35]
	v_pk_mul_f32 v[0:1], v[0:1], v[192:193]
	v_pk_mul_f32 v[16:17], v[18:19], v[16:17]
	v_cvt_pk_bf16_f32 v246, v22, v23
	v_cvt_pk_bf16_f32 v247, v16, v17
	v_mov_b32_e32 v16, v192
	v_mov_b32_e32 v17, v192
	v_pk_mul_f32 v[6:7], v[6:7], v[16:17]
	v_pk_mul_f32 v[2:3], v[2:3], v[16:17]
	v_lshl_add_u64 v[16:17], s[22:23], 1, v[32:33]
	v_lshl_add_u64 v[16:17], v[16:17], 0, s[72:73]
	v_lshl_add_u64 v[16:17], v[16:17], 0, v[64:65]
	v_mov_b32_e32 v244, v242
	v_mov_b32_e32 v245, v243
	global_store_dwordx4 v[16:17], v[244:247], off
	v_pk_fma_f32 v[22:23], v[4:5], v[90:91], v[94:95]
	v_fmac_f32_dpp v22, v4, v82 row_shr:1 row_mask:0xf bank_mask:0xf
	v_fmac_f32_dpp v22, v12, v82 row_shl:15 row_mask:0xf bank_mask:0xf
	v_fmac_f32_dpp v22, v4, v74 row_shr:2 row_mask:0xf bank_mask:0xf
	v_fmac_f32_dpp v22, v12, v74 row_shl:14 row_mask:0xf bank_mask:0xf
	v_fmac_f32_dpp v23, v5, v83 row_shr:1 row_mask:0xf bank_mask:0xf
	v_fmac_f32_dpp v23, v13, v83 row_shl:15 row_mask:0xf bank_mask:0xf
	v_fmac_f32_dpp v23, v5, v75 row_shr:2 row_mask:0xf bank_mask:0xf
	v_fmac_f32_dpp v23, v13, v75 row_shl:14 row_mask:0xf bank_mask:0xf
	v_pk_fma_f32 v[12:13], v[6:7], v[92:93], v[96:97]
	v_fmac_f32_dpp v12, v6, v84 row_shr:1 row_mask:0xf bank_mask:0xf
	v_fmac_f32_dpp v12, v14, v84 row_shl:15 row_mask:0xf bank_mask:0xf
	v_fmac_f32_dpp v12, v6, v76 row_shr:2 row_mask:0xf bank_mask:0xf
	v_fmac_f32_dpp v12, v14, v76 row_shl:14 row_mask:0xf bank_mask:0xf
	v_fmac_f32_dpp v13, v7, v85 row_shr:1 row_mask:0xf bank_mask:0xf
	v_fmac_f32_dpp v13, v15, v85 row_shl:15 row_mask:0xf bank_mask:0xf
	v_fmac_f32_dpp v13, v7, v77 row_shr:2 row_mask:0xf bank_mask:0xf
	v_fmac_f32_dpp v13, v15, v77 row_shl:14 row_mask:0xf bank_mask:0xf
	v_pk_fma_f32 v[18:19], v[0:1], v[66:67], v[70:71]
	v_fmac_f32_dpp v18, v0, v60 row_shr:1 row_mask:0xf bank_mask:0xf
	v_fmac_f32_dpp v18, v8, v60 row_shl:15 row_mask:0xf bank_mask:0xf
	v_fmac_f32_dpp v18, v0, v56 row_shr:2 row_mask:0xf bank_mask:0xf
	v_fmac_f32_dpp v18, v8, v56 row_shl:14 row_mask:0xf bank_mask:0xf
	v_fmac_f32_dpp v19, v1, v61 row_shr:1 row_mask:0xf bank_mask:0xf
	v_fmac_f32_dpp v19, v9, v61 row_shl:15 row_mask:0xf bank_mask:0xf
	v_fmac_f32_dpp v19, v1, v57 row_shr:2 row_mask:0xf bank_mask:0xf
	v_fmac_f32_dpp v19, v9, v57 row_shl:14 row_mask:0xf bank_mask:0xf
	v_pk_fma_f32 v[8:9], v[2:3], v[68:69], v[72:73]
	v_fmac_f32_dpp v8, v2, v62 row_shr:1 row_mask:0xf bank_mask:0xf
	v_fmac_f32_dpp v8, v10, v62 row_shl:15 row_mask:0xf bank_mask:0xf
	v_fmac_f32_dpp v8, v2, v58 row_shr:2 row_mask:0xf bank_mask:0xf
	v_fmac_f32_dpp v8, v10, v58 row_shl:14 row_mask:0xf bank_mask:0xf
	v_fmac_f32_dpp v9, v3, v63 row_shr:1 row_mask:0xf bank_mask:0xf
	v_fmac_f32_dpp v9, v11, v63 row_shl:15 row_mask:0xf bank_mask:0xf
	v_fmac_f32_dpp v9, v3, v59 row_shr:2 row_mask:0xf bank_mask:0xf
	v_fmac_f32_dpp v9, v11, v59 row_shl:14 row_mask:0xf bank_mask:0xf
	s_and_b64 vcc, exec, s[46:47]
	s_mov_b64 s[24:25], -1
	s_cbranch_vccnz .LBB0_319
	s_add_u32 s24, s55, s26
	s_addc_u32 s25, s58, s27
	v_mov_b64_e32 v[16:17], s[24:25]
	v_mad_u64_u32 v[16:17], s[24:25], v148, s0, v[16:17]
	s_mov_b64 s[24:25], 0

; DI unsigned pk2(float lo, float hi) { f32x2_t v = {lo, hi}; bf16x2_t b = __builtin_convertvector(v, bf16x2_t); return __builtin_bit_cast(unsigned, b); }
; template <int CTRL> DI float dppf(float v) { return __int_as_float(__builtin_amdgcn_mov_dpp(__float_as_int(v), CTRL, 0xf, 0xf, true)); }
;     DI void operator()(pg8::f32x4 (&acc)[2][2][4][2], const pg8::Unit& u, int wr, int wc, int fr, int fq) const {
;     ...
;                 for (int m = 0; m < 4; ++m) {
;                     float cv[2][4];
; #pragma unroll
;                     for (int bj = 0; bj < 2; ++bj) {
;                         const pg8::f32x4 cur = acc[ai][bj][m][n];
;                         pg8::f32x4 prv;
;                         if (m > 0) prv = acc[ai][bj][m > 0 ? m - 1 : 0][n]; else prv = (pg8::f32x4){hal[bj][0], hal[bj][1], hal[bj][2], hal[bj][3]};
; #pragma unroll
;                         for (int i = 0; i < 4; ++i) {
;                             const float q1 = dppf<0x121>(prv[i]), q2 = dppf<0x122>(prv[i]);
;                             const float p1 = __int_as_float(__builtin_amdgcn_update_dpp(__float_as_int(q1), __float_as_int(cur[i]), 0x111, 0xf, 0xf, false));
;                             const float p2 = __int_as_float(__builtin_amdgcn_update_dpp(__float_as_int(q2), __float_as_int(cur[i]), 0x112, 0xf, 0xf, false));
;                             cv[bj][i] = cb[bj][i] + w0[bj][i] * p2 + w1[bj][i] * p1 + w2[bj][i] * cur[i];
;                         }
;                     }
;                     float o[4];
; #pragma unroll
;                     for (int i = 0; i < 4; ++i) o[i] = gelu_tanh(cv[0][i]) * cv[1][i];
;                     const int row = u.pm * 256 + ai * 128 + wr * 64 + m * 16 + fr;
;                     v2u w; w.x = pk2(o[0], o[1]); w.y = pk2(o[2], o[3]);
;                     *(v2u*)(a_row(wsb, row) + u.pn * 128 + wc * 32 + 8 * fq + 4 * n) = w;
.LBB0_321:
	v_pk_mul_f32 v[32:33], v[22:23], v[22:23]
	v_pk_mul_f32 v[14:15], v[12:13], v[12:13]
	v_fmamk_f32 v32, v32, 0xbdd2d3e7, v175
	v_fmamk_f32 v33, v33, 0xbdd2d3e7, v175
	v_mul_f32_e32 v32, v22, v32
	v_mul_f32_e32 v33, v23, v33
	v_exp_f32_e32 v32, v32
	v_exp_f32_e32 v33, v33
	v_fmamk_f32 v14, v14, 0xbdd2d3e7, v175
	v_add_f32_e32 v32, 1.0, v32
	v_add_f32_e32 v33, 1.0, v33
	v_rcp_f32_e32 v32, v32
	v_rcp_f32_e32 v33, v33
	v_mul_f32_e32 v14, v12, v14
	v_pk_mul_f32 v[20:21], v[22:23], v[32:33]
	v_exp_f32_e32 v22, v14
	v_fmamk_f32 v14, v15, 0xbdd2d3e7, v175
	v_mul_f32_e32 v14, v13, v14
	v_exp_f32_e32 v23, v14
	v_pk_mul_f32 v[14:15], v[20:21], v[18:19]
	v_add_f32_e32 v18, 1.0, v22
	v_add_f32_e32 v19, 1.0, v23
	v_rcp_f32_e32 v18, v18
	v_rcp_f32_e32 v19, v19
	s_and_b64 vcc, exec, s[46:47]
	s_mov_b64 s[24:25], -1
	v_pk_mul_f32 v[10:11], v[12:13], v[18:19]
	v_pk_mul_f32 v[8:9], v[10:11], v[8:9]
	v_cvt_pk_bf16_f32 v246, v14, v15
	v_cvt_pk_bf16_f32 v247, v8, v9
	v_lshl_add_u64 v[8:9], s[22:23], 1, v[16:17]
	v_lshl_add_u64 v[8:9], v[8:9], 0, s[72:73]
	v_lshl_add_u64 v[8:9], v[8:9], 0, v[64:65]
	v_mov_b32_e32 v244, v248
	v_mov_b32_e32 v245, v249
	global_store_dwordx4 v[8:9], v[244:247], off
	v_pk_fma_f32 v[10:11], v[28:29], v[90:91], v[94:95]
	v_fmac_f32_dpp v10, v28, v82 row_shr:1 row_mask:0xf bank_mask:0xf
	v_fmac_f32_dpp v10, v4, v82 row_shl:15 row_mask:0xf bank_mask:0xf
	v_fmac_f32_dpp v10, v28, v74 row_shr:2 row_mask:0xf bank_mask:0xf
	v_fmac_f32_dpp v10, v4, v74 row_shl:14 row_mask:0xf bank_mask:0xf
	v_fmac_f32_dpp v11, v29, v83 row_shr:1 row_mask:0xf bank_mask:0xf
	v_fmac_f32_dpp v11, v5, v83 row_shl:15 row_mask:0xf bank_mask:0xf
	v_fmac_f32_dpp v11, v29, v75 row_shr:2 row_mask:0xf bank_mask:0xf
	v_fmac_f32_dpp v11, v5, v75 row_shl:14 row_mask:0xf bank_mask:0xf
	v_pk_fma_f32 v[4:5], v[30:31], v[92:93], v[96:97]
	v_fmac_f32_dpp v4, v30, v84 row_shr:1 row_mask:0xf bank_mask:0xf
	v_fmac_f32_dpp v4, v6, v84 row_shl:15 row_mask:0xf bank_mask:0xf
	v_fmac_f32_dpp v4, v30, v76 row_shr:2 row_mask:0xf bank_mask:0xf
	v_fmac_f32_dpp v4, v6, v76 row_shl:14 row_mask:0xf bank_mask:0xf
	v_fmac_f32_dpp v5, v31, v85 row_shr:1 row_mask:0xf bank_mask:0xf
	v_fmac_f32_dpp v5, v7, v85 row_shl:15 row_mask:0xf bank_mask:0xf
	v_fmac_f32_dpp v5, v31, v77 row_shr:2 row_mask:0xf bank_mask:0xf
	v_fmac_f32_dpp v5, v7, v77 row_shl:14 row_mask:0xf bank_mask:0xf
	v_pk_fma_f32 v[14:15], v[24:25], v[66:67], v[70:71]
	v_fmac_f32_dpp v14, v24, v60 row_shr:1 row_mask:0xf bank_mask:0xf
	v_fmac_f32_dpp v14, v0, v60 row_shl:15 row_mask:0xf bank_mask:0xf
	v_fmac_f32_dpp v14, v24, v56 row_shr:2 row_mask:0xf bank_mask:0xf
	v_fmac_f32_dpp v14, v0, v56 row_shl:14 row_mask:0xf bank_mask:0xf
	v_fmac_f32_dpp v15, v25, v61 row_shr:1 row_mask:0xf bank_mask:0xf
	v_fmac_f32_dpp v15, v1, v61 row_shl:15 row_mask:0xf bank_mask:0xf
	v_fmac_f32_dpp v15, v25, v57 row_shr:2 row_mask:0xf bank_mask:0xf
	v_fmac_f32_dpp v15, v1, v57 row_shl:14 row_mask:0xf bank_mask:0xf
	v_pk_fma_f32 v[0:1], v[26:27], v[68:69], v[72:73]
	v_fmac_f32_dpp v0, v26, v62 row_shr:1 row_mask:0xf bank_mask:0xf
	v_fmac_f32_dpp v0, v2, v62 row_shl:15 row_mask:0xf bank_mask:0xf
	v_fmac_f32_dpp v0, v26, v58 row_shr:2 row_mask:0xf bank_mask:0xf
	v_fmac_f32_dpp v0, v2, v58 row_shl:14 row_mask:0xf bank_mask:0xf
	v_fmac_f32_dpp v1, v27, v63 row_shr:1 row_mask:0xf bank_mask:0xf
	v_fmac_f32_dpp v1, v3, v63 row_shl:15 row_mask:0xf bank_mask:0xf
	v_fmac_f32_dpp v1, v27, v59 row_shr:2 row_mask:0xf bank_mask:0xf
	v_fmac_f32_dpp v1, v3, v59 row_shl:14 row_mask:0xf bank_mask:0xf
	s_cbranch_vccnz .LBB0_323
	s_add_u32 s24, s55, s26
	s_addc_u32 s25, s58, s27
	v_mov_b64_e32 v[8:9], s[24:25]
	v_mad_u64_u32 v[8:9], s[24:25], v149, s0, v[8:9]
	s_mov_b64 s[24:25], 0

; DI unsigned pk2(float lo, float hi) { f32x2_t v = {lo, hi}; bf16x2_t b = __builtin_convertvector(v, bf16x2_t); return __builtin_bit_cast(unsigned, b); }
; DI float gelu_tanh(float x) {
;     constexpr float C1 = -2.0f * 0.7978845608028654f * LOG2E, C2 = C1 * 0.044715f;
;     const float e = __builtin_amdgcn_exp2f(x * __builtin_fmaf(x * x, C2, C1));
;     return x * __builtin_amdgcn_rcpf(1.0f + e);
; }
;     DI void operator()(pg8::f32x4 (&acc)[2][2][4][2], const pg8::Unit& u, int wr, int wc, int fr, int fq) const {
;     ...
;                             cv[bj][i] = cb[bj][i] + w0[bj][i] * p2 + w1[bj][i] * p1 + w2[bj][i] * cur[i];
;                         }
;                     }
;                     float o[4];
; #pragma unroll
;                     for (int i = 0; i < 4; ++i) o[i] = gelu_tanh(cv[0][i]) * cv[1][i];
;                     const int row = u.pm * 256 + ai * 128 + wr * 64 + m * 16 + fr;
;                     v2u w; w.x = pk2(o[0], o[1]); w.y = pk2(o[2], o[3]);
;                     *(v2u*)(a_row(wsb, row) + u.pn * 128 + wc * 32 + 8 * fq + 4 * n) = w;
.LBB0_325:
	v_pk_mul_f32 v[12:13], v[10:11], v[10:11]
	v_pk_mul_f32 v[6:7], v[4:5], v[4:5]
	v_fmamk_f32 v12, v12, 0xbdd2d3e7, v175
	v_fmamk_f32 v13, v13, 0xbdd2d3e7, v175
	v_mul_f32_e32 v12, v10, v12
	v_mul_f32_e32 v13, v11, v13
	v_exp_f32_e32 v12, v12
	v_exp_f32_e32 v13, v13
	v_fmamk_f32 v6, v6, 0xbdd2d3e7, v175
	v_mul_f32_e32 v6, v4, v6
	v_add_f32_e32 v12, 1.0, v12
	v_add_f32_e32 v13, 1.0, v13
	v_rcp_f32_e32 v12, v12
	v_rcp_f32_e32 v13, v13
	s_nop 0
	v_pk_mul_f32 v[10:11], v[10:11], v[12:13]
	v_exp_f32_e32 v12, v6
	v_fmamk_f32 v6, v7, 0xbdd2d3e7, v175
	v_mul_f32_e32 v6, v5, v6
	v_exp_f32_e32 v7, v6
	v_pk_mul_f32 v[10:11], v[10:11], v[14:15]
	v_add_f32_e32 v7, 1.0, v7
	v_cvt_pk_bf16_f32 v246, v10, v11
	v_add_f32_e32 v10, 1.0, v12
	v_rcp_f32_e32 v10, v10
	v_rcp_f32_e32 v11, v7
	s_andn2_b64 vcc, exec, s[40:41]
	v_pk_mul_f32 v[2:3], v[4:5], v[10:11]
	s_nop 0
	v_pk_mul_f32 v[0:1], v[2:3], v[0:1]
	s_nop 0
	v_cvt_pk_bf16_f32 v247, v0, v1
	v_lshl_add_u64 v[0:1], s[22:23], 1, v[8:9]
	v_lshl_add_u64 v[0:1], v[0:1], 0, s[72:73]
	v_lshl_add_u64 v[0:1], v[0:1], 0, v[64:65]
	s_mov_b64 s[22:23], -1
	v_mov_b32_e32 v244, v250
	v_mov_b32_e32 v245, v251
	global_store_dwordx4 v[0:1], v[244:247], off
	s_cbranch_vccnz .LBB0_238
	s_and_b64 vcc, exec, s[42:43]
	s_cbranch_vccnz .LBB0_237
	s_barrier
	s_branch .LBB0_237
